# retention-output units: the 8 row-scaled Q chunk loads of the forward-state block issued together (were serialized load-wait-scale-store round trips)
# baseline (speedup 1.0000x reference)
.LBB0_497:
	s_andn2_b64 vcc, exec, s[0:1]
	s_cbranch_vccnz .LBB0_704
	v_readlane_b32 s0, v255, 25
	s_and_b32 s78, s76, 3
	s_lshl_b32 s0, s0, 3
	v_readlane_b32 s1, v255, 26
	s_or_b32 s0, s78, s0
	s_ashr_i32 s22, s76, 2
	s_ashr_i32 s1, s0, 31
	v_readlane_b32 s4, v254, 30
	s_lshl_b32 s44, s22, 7
	s_and_b32 s23, s22, 31
	s_lshl_b64 s[0:1], s[0:1], 2
	v_readlane_b32 s18, v254, 44
	v_readlane_b32 s19, v254, 45
	s_add_u32 s2, s18, s0
	s_addc_u32 s3, s19, s1
	s_mul_i32 s0, s22, 0xa0000
	v_mov_b32_e32 v64, v139
	s_mul_hi_i32 s1, s44, 0x1400
	s_add_u32 s0, s92, s0
	s_addc_u32 s1, s93, s1
	s_lshl_b32 s34, s78, 8
	s_waitcnt vmcnt(0) lgkmcnt(0)
	v_lshlrev_b32_e32 v0, 3, v64
	s_add_u32 s40, s0, s34
	v_and_b32_e32 v0, 56, v0
	s_waitcnt vmcnt(0)
	v_bfe_u32 v101, v64, 3, 5
	s_addc_u32 s41, s1, 0
	v_lshlrev_b32_e32 v136, 1, v0
	v_mul_u32_u24_e32 v2, 0xa00, v101
	v_readlane_b32 s8, v254, 34
	v_readlane_b32 s9, v254, 35
	v_readlane_b32 s10, v254, 36
	v_readlane_b32 s11, v254, 37
	v_readlane_b32 s12, v254, 38
	v_readlane_b32 s13, v254, 39
	v_lshl_add_u64 v[0:1], s[40:41], 0, v[136:137]
	v_lshlrev_b32_e32 v80, 1, v2
	v_mov_b32_e32 v81, v137
	v_lshl_add_u64 v[24:25], v[0:1], 0, v[80:81]
	s_mov_b64 s[8:9], 0x28000
	s_mov_b64 s[10:11], 0x50000
	s_mov_b64 s[12:13], 0x78000
	v_lshl_add_u64 v[52:53], v[24:25], 0, s[8:9]
	v_lshl_add_u64 v[56:57], v[24:25], 0, s[10:11]
	v_lshl_add_u64 v[60:61], v[24:25], 0, s[12:13]
	global_load_dwordx4 v[0:3], v[52:53], off offset:832
	global_load_dwordx4 v[4:7], v[24:25], off offset:832
	global_load_dwordx4 v[8:11], v[24:25], off offset:960
	global_load_dwordx4 v[12:15], v[24:25], off offset:1856
	global_load_dwordx4 v[16:19], v[24:25], off offset:1984
	global_load_dwordx4 v[20:23], v[56:57], off offset:832
	s_nop 0
	global_load_dwordx4 v[24:27], v[60:61], off offset:832
	global_load_dwordx4 v[28:31], v[52:53], off offset:960
	global_load_dwordx4 v[32:35], v[56:57], off offset:960
	global_load_dwordx4 v[36:39], v[60:61], off offset:960
	global_load_dwordx4 v[40:43], v[52:53], off offset:1856
	global_load_dwordx4 v[44:47], v[56:57], off offset:1856
	global_load_dwordx4 v[48:51], v[60:61], off offset:1856
	s_nop 0
	global_load_dwordx4 v[52:55], v[52:53], off offset:1984
	s_nop 0
	global_load_dwordx4 v[56:59], v[56:57], off offset:1984
	s_nop 0
	global_load_dwordx4 v[60:63], v[60:61], off offset:1984
	s_nop 0
	global_load_dword v78, v137, s[2:3]
	global_load_dword v79, v137, s[2:3] offset:16
	v_lshrrev_b32_e32 v65, 1, v64
	v_readlane_b32 s5, v254, 31
	v_and_b32_e32 v92, 31, v64
	v_and_b32_e32 v95, 64, v65
	v_mov_b32_e32 v83, s24
	v_lshlrev_b32_e32 v66, 4, v64
	v_or_b32_e32 v67, v95, v92
	s_movk_i32 s5, 0x90
	v_and_b32_e32 v82, 0x70, v66
	v_mul_u32_u24_e32 v103, 0x90, v101
	v_and_b32_e32 v66, 16, v65
	v_mad_u32_u24 v67, v67, s5, v83
	v_add3_u32 v99, s24, v82, v103
	v_add_u32_e32 v97, v67, v66
	v_add_u32_e32 v100, 0xd800, v99
	v_bfe_u32 v96, v64, 6, 1
	v_lshlrev_b32_e32 v93, 6, v96
	v_or_b32_e32 v94, v93, v92
	s_add_i32 s80, s24, 0x4800
	v_cmp_eq_u32_e32 vcc, 0, v96
	s_add_i32 s82, s24, 0x9000
	s_add_i32 s83, s24, 0xd800
	s_and_b32 s38, s22, 1
	s_cmp_lt_i32 s22, 64
	s_mov_b32 s4, 0x13c20000
	v_readlane_b32 s6, v254, 32
	v_readlane_b32 s7, v254, 33
	v_readlane_b32 s14, v254, 40
	v_readlane_b32 s15, v254, 41
	v_readlane_b32 s16, v254, 42
	v_readlane_b32 s17, v254, 43
	s_waitcnt vmcnt(16)
	ds_write_b128 v99, v[4:7]
	s_waitcnt vmcnt(15)
	ds_write_b128 v99, v[8:11] offset:18432
	s_waitcnt vmcnt(14)
	ds_write_b128 v99, v[12:15] offset:36864
	s_waitcnt vmcnt(13)
	ds_write_b128 v99, v[16:19] offset:55296
	ds_write_b128 v99, v[0:3] offset:4608
	s_waitcnt vmcnt(12)
	ds_write_b128 v99, v[20:23] offset:9216
	s_waitcnt vmcnt(11)
	ds_write_b128 v99, v[24:27] offset:13824
	s_waitcnt vmcnt(10)
	ds_write_b128 v99, v[28:31] offset:23040
	s_waitcnt vmcnt(9)
	ds_write_b128 v99, v[32:35] offset:27648
	s_waitcnt vmcnt(8)
	ds_write_b128 v99, v[36:39] offset:32256
	s_waitcnt vmcnt(7)
	ds_write_b128 v99, v[40:43] offset:41472
	s_waitcnt vmcnt(6)
	ds_write_b128 v99, v[44:47] offset:46080
	s_waitcnt vmcnt(5)
	ds_write_b128 v99, v[48:51] offset:50688
	s_waitcnt vmcnt(4)
	ds_write_b128 v99, v[52:55] offset:59904
	s_waitcnt vmcnt(3)
	ds_write_b128 v99, v[56:59] offset:64512
	s_waitcnt vmcnt(2)
	ds_write_b128 v100, v[60:63] offset:13824
	s_waitcnt lgkmcnt(0)
	s_barrier
	ds_read_b128 v[0:3], v97
	v_mad_u32_u24 v4, v94, s5, v83
	v_add_u32_e32 v98, v4, v66
	ds_read_b128 v[4:7], v98 offset:36864
	ds_read_b128 v[66:69], v97 offset:32
	ds_read_b128 v[70:73], v98 offset:36896
	ds_read_b128 v[8:11], v98 offset:41472
	ds_read_b128 v[74:77], v98 offset:41504
	s_waitcnt lgkmcnt(4)
	v_mfma_f32_32x32x16_bf16 v[48:63], v[0:3], v[4:7], 0
	s_waitcnt lgkmcnt(1)
	v_mfma_f32_32x32x16_bf16 v[32:47], v[0:3], v[8:11], 0
	ds_read_b128 v[0:3], v97 offset:4608
	ds_read_b128 v[84:87], v97 offset:4640
	s_waitcnt lgkmcnt(1)
	v_mfma_f32_32x32x16_bf16 v[16:31], v[0:3], v[4:7], 0
	v_mfma_f32_32x32x16_bf16 v[0:15], v[0:3], v[8:11], 0
	v_mfma_f32_32x32x16_bf16 v[48:63], v[66:69], v[70:73], v[48:63]
	v_mfma_f32_32x32x16_bf16 v[32:47], v[66:69], v[74:77], v[32:47]
	s_waitcnt lgkmcnt(0)
	v_mfma_f32_32x32x16_bf16 v[16:31], v[84:87], v[70:73], v[16:31]
	v_mfma_f32_32x32x16_bf16 v[0:15], v[84:87], v[74:77], v[0:15]
	ds_read_b128 v[66:69], v97 offset:64
	ds_read_b128 v[70:73], v98 offset:36928
	ds_read_b128 v[74:77], v97 offset:96
	ds_read_b128 v[84:87], v98 offset:36960
	ds_read_b128 v[88:91], v98 offset:41536
	ds_read_b128 v[104:107], v98 offset:41568
	s_waitcnt lgkmcnt(4)
	v_mfma_f32_32x32x16_bf16 v[48:63], v[66:69], v[70:73], v[48:63]
	s_waitcnt lgkmcnt(1)
	v_mfma_f32_32x32x16_bf16 v[32:47], v[66:69], v[88:91], v[32:47]
	ds_read_b128 v[66:69], v97 offset:4672
	ds_read_b128 v[108:111], v97 offset:4704
	s_waitcnt lgkmcnt(1)
	v_mfma_f32_32x32x16_bf16 v[16:31], v[66:69], v[70:73], v[16:31]
	v_mfma_f32_32x32x16_bf16 v[0:15], v[66:69], v[88:91], v[0:15]
	s_waitcnt vmcnt(0)
	v_mul_f32_e32 v68, 0x3fb8aa3b, v79
	v_exp_f32_e32 v72, v68
	ds_read_b128 v[68:71], v97 offset:18432
	v_mul_f32_e32 v66, 0x3fb8aa3b, v78
	v_lshrrev_b32_e32 v67, 3, v64
	v_mul_f32_e32 v102, 0xbfb8aa3b, v72
	v_and_or_b32 v95, v67, 4, v95
	v_mfma_f32_32x32x16_bf16 v[48:63], v[74:77], v[84:87], v[48:63]
	v_exp_f32_e32 v66, v66
	v_mul_u32_u24_e32 v67, 0x90, v95
	v_mul_f32_e32 v66, 0xbfb8aa3b, v66
	v_mfma_f32_32x32x16_bf16 v[32:47], v[74:77], v[104:107], v[32:47]
	s_waitcnt lgkmcnt(1)
	v_mfma_f32_32x32x16_bf16 v[16:31], v[108:111], v[84:87], v[16:31]
	v_mfma_f32_32x32x16_bf16 v[0:15], v[108:111], v[104:107], v[0:15]
	ds_read_b128 v[72:75], v98 offset:55296
	ds_read_b128 v[76:79], v97 offset:18464
	ds_read_b128 v[84:87], v97 offset:23040
	ds_read_b128 v[88:91], v97 offset:23072
	ds_read_b128 v[104:107], v98 offset:55328
	ds_read_b128 v[108:111], v98 offset:59904
	ds_read_b128 v[112:115], v98 offset:59936
	ds_read_b128 v[116:119], v97 offset:18496
	ds_read_b128 v[120:123], v97 offset:18528
	ds_read_b128 v[124:127], v97 offset:23104
	ds_read_b128 v[128:131], v97 offset:23136
	ds_read_b128 v[132:135], v98 offset:55360
	ds_read_b128 v[142:145], v98 offset:55392
	ds_read_b128 v[146:149], v98 offset:59968
	ds_read_b128 v[150:153], v98 offset:60000
	s_waitcnt lgkmcnt(0)
	s_barrier
	v_mfma_f32_32x32x16_bf16 v[48:63], v[68:71], v[72:75], v[48:63]
	v_mfma_f32_32x32x16_bf16 v[48:63], v[76:79], v[104:107], v[48:63]
	v_mfma_f32_32x32x16_bf16 v[32:47], v[68:71], v[108:111], v[32:47]
	v_mov_b32_e32 v68, s80
	v_cndmask_b32_e32 v69, v68, v83, vcc
	v_sub_u32_e32 v68, v95, v94
	v_lshlrev_b32_e32 v71, 1, v92
	v_sub_u32_e32 v70, 0, v68
	v_max_i32_e32 v70, v68, v70
	v_mfma_f32_32x32x16_bf16 v[48:63], v[116:119], v[132:135], v[48:63]
	v_cvt_f32_u32_e32 v70, v70
	v_cmp_lt_i32_e32 vcc, 0, v68
	v_add3_u32 v67, v69, v67, v71
	v_cmp_gt_i32_e64 s[0:1], 0, v68
	v_cndmask_b32_e32 v83, v102, v66, vcc
	v_mul_f32_e32 v70, v83, v70
	v_exp_f32_e32 v70, v70
	v_mfma_f32_32x32x16_bf16 v[48:63], v[120:123], v[142:145], v[48:63]
	v_cmp_ne_u32_e32 vcc, 0, v68
	s_nop 1
	v_cndmask_b32_e32 v69, 2.0, v70, vcc
	v_add_co_u32_e32 v70, vcc, 1, v68
	v_sub_u32_e32 v71, 0, v70
	v_max_i32_e32 v71, v70, v71
	v_cvt_f32_u32_e32 v71, v71
	s_nop 3
	v_mul_f32_e32 v48, 0x3db504f3, v48
	v_mfma_f32_32x32x16_bf16 v[16:31], v[84:87], v[72:75], v[16:31]
	v_mul_f32_e32 v72, v48, v69
	v_cndmask_b32_e64 v48, v66, v102, s[0:1]
	v_mul_f32_e32 v48, v48, v71
	v_exp_f32_e32 v48, v48
	v_cvt_pk_bf16_f32 v71, v72, s0
	ds_write_b16 v67, v71
	v_mul_f32_e32 v49, 0x3db504f3, v49
	v_cndmask_b32_e64 v71, v48, 2.0, vcc
	v_mul_f32_e32 v49, v49, v71
	v_add_u32_e32 v71, 2, v68
	v_sub_u32_e32 v72, 0, v71
	v_max_i32_e32 v72, v71, v72
	v_cvt_f32_u32_e32 v72, v72
	v_cmp_lt_i32_e32 vcc, -2, v68
	v_cvt_pk_bf16_f32 v73, v49, s0
	v_mul_f32_e32 v50, 0x3db504f3, v50
	v_cndmask_b32_e32 v49, v102, v66, vcc
	v_mul_f32_e32 v49, v49, v72
	v_exp_f32_e32 v49, v49
	v_cmp_ne_u32_e32 vcc, 0, v71
	ds_write_b16 v67, v73 offset:144
	v_mul_f32_e32 v51, 0x3db504f3, v51
	v_cndmask_b32_e32 v72, 2.0, v49, vcc
	v_mul_f32_e32 v50, v50, v72
	v_add_u32_e32 v72, 3, v68
	v_sub_u32_e32 v73, 0, v72
	v_max_i32_e32 v73, v72, v73
	v_cvt_f32_u32_e32 v73, v73
	v_cmp_lt_i32_e32 vcc, -3, v68
	v_cvt_pk_bf16_f32 v74, v50, s0
	ds_write_b16 v67, v74 offset:288
	v_cndmask_b32_e32 v50, v102, v66, vcc
	v_mul_f32_e32 v50, v50, v73
	v_exp_f32_e32 v50, v50
	v_cmp_ne_u32_e32 vcc, 0, v72
	v_mul_f32_e32 v52, 0x3db504f3, v52
	v_mfma_f32_32x32x16_bf16 v[32:47], v[76:79], v[112:115], v[32:47]
	v_cndmask_b32_e32 v73, 2.0, v50, vcc
	v_mul_f32_e32 v51, v51, v73
	v_add_u32_e32 v73, 8, v68
	v_sub_u32_e32 v74, 0, v73
	v_max_i32_e32 v74, v73, v74
	v_cvt_f32_u32_e32 v74, v74
	v_cmp_lt_i32_e32 vcc, -8, v68
	v_cvt_pk_bf16_f32 v75, v51, s0
	ds_write_b16 v67, v75 offset:432
	v_cndmask_b32_e32 v51, v102, v66, vcc
	v_mul_f32_e32 v51, v51, v74
	v_exp_f32_e32 v51, v51
	v_cmp_ne_u32_e32 vcc, 0, v73
	v_mul_f32_e32 v53, 0x3db504f3, v53
	v_mul_f32_e32 v54, 0x3db504f3, v54
	v_cndmask_b32_e32 v74, 2.0, v51, vcc
	v_mul_f32_e32 v52, v52, v74
	v_add_u32_e32 v74, 9, v68
	v_sub_u32_e32 v75, 0, v74
	v_max_i32_e32 v75, v74, v75
	v_cvt_f32_u32_e32 v75, v75
	v_cmp_lt_i32_e32 vcc, -9, v68
	v_cvt_pk_bf16_f32 v76, v52, s0
	ds_write_b16 v67, v76 offset:1152
	v_cndmask_b32_e32 v52, v102, v66, vcc
	v_mul_f32_e32 v52, v52, v75
	v_add_u32_e32 v76, 10, v68
	v_exp_f32_e32 v52, v52
	v_sub_u32_e32 v77, 0, v76
	v_max_i32_e32 v77, v76, v77
	v_cvt_f32_u32_e32 v77, v77
	v_cmp_ne_u32_e32 vcc, 0, v74
	v_mul_f32_e32 v55, 0x3db504f3, v55
	v_mul_f32_e32 v56, 0x3db504f3, v56
	v_cndmask_b32_e32 v75, 2.0, v52, vcc
	v_cmp_lt_i32_e32 vcc, -10, v68
	v_mul_f32_e32 v75, v53, v75
	v_cvt_pk_bf16_f32 v75, v75, s0
	v_cndmask_b32_e32 v53, v102, v66, vcc
	v_mul_f32_e32 v53, v53, v77
	v_add_u32_e32 v77, 11, v68
	v_exp_f32_e32 v53, v53
	v_sub_u32_e32 v78, 0, v77
	v_max_i32_e32 v78, v77, v78
	v_cvt_f32_u32_e32 v78, v78
	v_cmp_ne_u32_e32 vcc, 0, v76
	ds_write_b16 v67, v75 offset:1296
	v_mfma_f32_32x32x16_bf16 v[0:15], v[84:87], v[108:111], v[0:15]
	v_cndmask_b32_e32 v75, 2.0, v53, vcc
	v_cmp_lt_i32_e32 vcc, -11, v68
	v_mul_f32_e32 v75, v54, v75
	v_cvt_pk_bf16_f32 v75, v75, s0
	v_cndmask_b32_e32 v54, v102, v66, vcc
	v_mul_f32_e32 v54, v54, v78
	v_add_u32_e32 v78, 16, v68
	v_exp_f32_e32 v54, v54
	v_sub_u32_e32 v79, 0, v78
	v_max_i32_e32 v79, v78, v79
	v_cvt_f32_u32_e32 v79, v79
	v_cmp_ne_u32_e32 vcc, 0, v77
	ds_write_b16 v67, v75 offset:1440
	v_mul_f32_e32 v57, 0x3db504f3, v57
	v_cndmask_b32_e32 v75, 2.0, v54, vcc
	v_cmp_lt_i32_e32 vcc, -16, v68
	v_mul_f32_e32 v75, v55, v75
	v_cvt_pk_bf16_f32 v75, v75, s0
	v_cndmask_b32_e32 v55, v102, v66, vcc
	v_mul_f32_e32 v55, v55, v79
	v_add_u32_e32 v79, 17, v68
	v_exp_f32_e32 v55, v55
	v_sub_u32_e32 v83, 0, v79
	v_max_i32_e32 v83, v79, v83
	v_cvt_f32_u32_e32 v83, v83
	v_cmp_ne_u32_e32 vcc, 0, v78
	s_movk_i32 s0, 0xffef
	ds_write_b16 v67, v75 offset:1584
	v_cndmask_b32_e32 v75, 2.0, v55, vcc
	v_cmp_lt_i32_e32 vcc, s0, v68
	v_mul_f32_e32 v75, v56, v75
	v_cvt_pk_bf16_f32 v75, v75, s0
	v_cndmask_b32_e32 v56, v102, v66, vcc
	v_mul_f32_e32 v56, v56, v83
	v_add_u32_e32 v83, 18, v68
	v_exp_f32_e32 v56, v56
	v_sub_u32_e32 v84, 0, v83
	v_max_i32_e32 v84, v83, v84
	v_cvt_f32_u32_e32 v84, v84
	v_cmp_ne_u32_e32 vcc, 0, v79
	s_movk_i32 s0, 0xffee
	ds_write_b16 v67, v75 offset:2304
	v_cndmask_b32_e32 v75, 2.0, v56, vcc
	v_cmp_lt_i32_e32 vcc, s0, v68
	v_mul_f32_e32 v75, v57, v75
	v_cvt_pk_bf16_f32 v75, v75, s0
	v_cndmask_b32_e32 v57, v102, v66, vcc
	v_mul_f32_e32 v57, v57, v84
	v_add_u32_e32 v84, 19, v68
	v_exp_f32_e32 v57, v57
	v_sub_u32_e32 v85, 0, v84
	v_max_i32_e32 v85, v84, v85
	v_cvt_f32_u32_e32 v85, v85
	v_cmp_ne_u32_e32 vcc, 0, v83
	s_movk_i32 s0, 0xffed
	ds_write_b16 v67, v75 offset:2448
	v_cndmask_b32_e32 v75, 2.0, v57, vcc
	v_mul_f32_e32 v58, 0x3db504f3, v58
	v_cmp_lt_i32_e32 vcc, s0, v68
	v_mul_f32_e32 v75, v58, v75
	v_cvt_pk_bf16_f32 v75, v75, s0
	v_cndmask_b32_e32 v58, v102, v66, vcc
	v_mul_f32_e32 v58, v58, v85
	v_add_u32_e32 v85, 24, v68
	v_exp_f32_e32 v58, v58
	v_sub_u32_e32 v86, 0, v85
	v_max_i32_e32 v86, v85, v86
	v_cvt_f32_u32_e32 v86, v86
	v_cmp_ne_u32_e32 vcc, 0, v84
	s_movk_i32 s0, 0xffe8
	ds_write_b16 v67, v75 offset:2592
	v_cndmask_b32_e32 v75, 2.0, v58, vcc
	v_mul_f32_e32 v59, 0x3db504f3, v59
	v_cmp_lt_i32_e32 vcc, s0, v68
	v_mul_f32_e32 v75, v59, v75
	v_cvt_pk_bf16_f32 v75, v75, s0
	v_cndmask_b32_e32 v59, v102, v66, vcc
	v_mul_f32_e32 v59, v59, v86
	v_add_u32_e32 v86, 25, v68
	v_exp_f32_e32 v59, v59
	v_sub_u32_e32 v87, 0, v86
	v_max_i32_e32 v87, v86, v87
	v_cvt_f32_u32_e32 v87, v87
	v_cmp_ne_u32_e32 vcc, 0, v85
	s_movk_i32 s0, 0xffe7
	ds_write_b16 v67, v75 offset:2736
	v_cndmask_b32_e32 v75, 2.0, v59, vcc
	v_mul_f32_e32 v60, 0x3db504f3, v60
	v_cmp_lt_i32_e32 vcc, s0, v68
	v_mul_f32_e32 v75, v60, v75
	v_mfma_f32_32x32x16_bf16 v[16:31], v[88:91], v[104:107], v[16:31]
	v_cndmask_b32_e32 v60, v102, v66, vcc
	v_mul_f32_e32 v60, v60, v87
	v_add_u32_e32 v87, 26, v68
	v_exp_f32_e32 v60, v60
	v_cvt_pk_bf16_f32 v75, v75, s0
	v_cmp_ne_u32_e32 vcc, 0, v86
	s_movk_i32 s0, 0xffe6
	v_mfma_f32_32x32x16_bf16 v[0:15], v[88:91], v[112:115], v[0:15]
	v_sub_u32_e32 v88, 0, v87
	v_max_i32_e32 v88, v87, v88
	v_cvt_f32_u32_e32 v88, v88
	ds_write_b16 v67, v75 offset:3456
	v_cndmask_b32_e32 v75, 2.0, v60, vcc
	v_mul_f32_e32 v61, 0x3db504f3, v61
	v_cmp_lt_i32_e32 vcc, s0, v68
	v_mul_f32_e32 v75, v61, v75
	v_cvt_pk_bf16_f32 v75, v75, s0
	v_cndmask_b32_e32 v61, v102, v66, vcc
	v_mul_f32_e32 v61, v61, v88
	v_add_u32_e32 v88, 27, v68
	v_exp_f32_e32 v61, v61
	v_sub_u32_e32 v89, 0, v88
	v_max_i32_e32 v89, v88, v89
	v_cvt_f32_u32_e32 v89, v89
	v_cmp_ne_u32_e32 vcc, 0, v87
	s_movk_i32 s0, 0xffe5
	ds_write_b16 v67, v75 offset:3600
	v_cndmask_b32_e32 v75, 2.0, v61, vcc
	v_mul_f32_e32 v62, 0x3db504f3, v62
	v_cmp_lt_i32_e32 vcc, s0, v68
	v_mul_f32_e32 v75, v62, v75
	v_mfma_f32_32x32x16_bf16 v[32:47], v[116:119], v[146:149], v[32:47]
	v_cndmask_b32_e32 v62, v102, v66, vcc
	v_mul_f32_e32 v62, v62, v89
	v_exp_f32_e32 v62, v62
	v_subrev_u32_e32 v89, 32, v68
	v_sub_u32_e32 v90, 32, v68
	v_max_i32_e32 v89, v89, v90
	v_cvt_f32_u32_e32 v89, v89
	v_cvt_pk_bf16_f32 v75, v75, s0
	v_cmp_ne_u32_e32 vcc, 0, v88
	ds_write_b16 v67, v75 offset:3744
	v_mul_f32_e32 v63, 0x3db504f3, v63
	v_cndmask_b32_e32 v75, 2.0, v62, vcc
	v_cmp_lt_i32_e32 vcc, 32, v68
	v_mul_f32_e32 v63, v63, v75
	v_mfma_f32_32x32x16_bf16 v[32:47], v[120:123], v[150:153], v[32:47]
	v_cndmask_b32_e32 v75, v102, v66, vcc
	v_mul_f32_e32 v75, v75, v89
	v_exp_f32_e32 v75, v75
	v_cvt_pk_bf16_f32 v63, v63, s0
	v_cmp_ne_u32_e32 vcc, 32, v68
	ds_write_b16 v67, v63 offset:3888
	v_sub_u32_e32 v89, 31, v68
	v_cndmask_b32_e32 v63, 2.0, v75, vcc
	v_subrev_u32_e32 v75, 31, v68
	v_max_i32_e32 v75, v75, v89
	v_cvt_f32_u32_e32 v75, v75
	s_nop 0
	v_mul_f32_e32 v32, 0x3db504f3, v32
	v_cmp_lt_i32_e32 vcc, 31, v68
	v_mul_f32_e32 v32, v32, v63
	v_cvt_pk_bf16_f32 v32, v32, s0
	v_cndmask_b32_e32 v63, v102, v66, vcc
	v_mul_f32_e32 v63, v63, v75
	v_exp_f32_e32 v63, v63
	v_cmp_ne_u32_e32 vcc, 32, v70
	ds_write_b16 v67, v32 offset:64
	v_sub_u32_e32 v70, 30, v68
	v_cndmask_b32_e32 v32, 2.0, v63, vcc
	v_subrev_u32_e32 v63, 30, v68
	v_max_i32_e32 v63, v63, v70
	v_cvt_f32_u32_e32 v63, v63
	v_mul_f32_e32 v33, 0x3db504f3, v33
	v_cmp_lt_i32_e32 vcc, 30, v68
	v_mul_f32_e32 v32, v33, v32
	v_cvt_pk_bf16_f32 v32, v32, s0
	v_cndmask_b32_e32 v33, v102, v66, vcc
	v_mul_f32_e32 v33, v33, v63
	v_exp_f32_e32 v33, v33
	v_cmp_ne_u32_e32 vcc, 32, v71
	ds_write_b16 v67, v32 offset:208
	v_sub_u32_e32 v63, 29, v68
	v_cndmask_b32_e32 v32, 2.0, v33, vcc
	v_mul_f32_e32 v33, 0x3db504f3, v34
	v_subrev_u32_e32 v34, 29, v68
	v_max_i32_e32 v34, v34, v63
	v_cvt_f32_u32_e32 v34, v34
	v_cmp_lt_i32_e32 vcc, 29, v68
	v_mul_f32_e32 v32, v33, v32
	v_cvt_pk_bf16_f32 v32, v32, s0
	v_cndmask_b32_e32 v33, v102, v66, vcc
	v_mul_f32_e32 v33, v33, v34
	v_exp_f32_e32 v33, v33
	v_cmp_ne_u32_e32 vcc, 32, v72
	ds_write_b16 v67, v32 offset:352
	v_subrev_u32_e32 v34, 24, v68
	v_cndmask_b32_e32 v32, 2.0, v33, vcc
	v_mul_f32_e32 v33, 0x3db504f3, v35
	v_sub_u32_e32 v35, 24, v68
	v_max_i32_e32 v34, v34, v35
	v_cvt_f32_u32_e32 v34, v34
	v_cmp_lt_i32_e32 vcc, 24, v68
	v_mul_f32_e32 v32, v33, v32
	v_sub_u32_e32 v35, 23, v68
	v_cndmask_b32_e32 v33, v102, v66, vcc
	v_mul_f32_e32 v33, v33, v34
	v_exp_f32_e32 v33, v33
	v_subrev_u32_e32 v34, 23, v68
	v_max_i32_e32 v34, v34, v35
	v_cvt_f32_u32_e32 v34, v34
	v_cvt_pk_bf16_f32 v32, v32, s0
	v_cmp_ne_u32_e32 vcc, 32, v73
	ds_write_b16 v67, v32 offset:496
	v_sub_u32_e32 v35, 22, v68
	v_cndmask_b32_e32 v32, 2.0, v33, vcc
	v_mul_f32_e32 v33, 0x3db504f3, v36
	v_cmp_lt_i32_e32 vcc, 23, v68
	v_mul_f32_e32 v32, v33, v32
	v_cvt_pk_bf16_f32 v32, v32, s0
	v_cndmask_b32_e32 v33, v102, v66, vcc
	v_mul_f32_e32 v33, v33, v34
	v_exp_f32_e32 v33, v33
	v_subrev_u32_e32 v34, 22, v68
	v_max_i32_e32 v34, v34, v35
	v_cvt_f32_u32_e32 v34, v34
	v_cmp_ne_u32_e32 vcc, 32, v74
	ds_write_b16 v67, v32 offset:1216
	v_sub_u32_e32 v35, 21, v68
	v_cndmask_b32_e32 v32, 2.0, v33, vcc
	v_mul_f32_e32 v33, 0x3db504f3, v37
	v_cmp_lt_i32_e32 vcc, 22, v68
	v_mul_f32_e32 v32, v33, v32
	v_cvt_pk_bf16_f32 v32, v32, s0
	v_cndmask_b32_e32 v33, v102, v66, vcc
	v_mul_f32_e32 v33, v33, v34
	v_exp_f32_e32 v33, v33
	v_subrev_u32_e32 v34, 21, v68
	v_max_i32_e32 v34, v34, v35
	v_cvt_f32_u32_e32 v34, v34
	v_cmp_ne_u32_e32 vcc, 32, v76
	ds_write_b16 v67, v32 offset:1360
	v_sub_u32_e32 v35, 16, v68
	v_cndmask_b32_e32 v32, 2.0, v33, vcc
	v_mul_f32_e32 v33, 0x3db504f3, v38
	v_cmp_lt_i32_e32 vcc, 21, v68
	v_mul_f32_e32 v32, v33, v32
	v_cvt_pk_bf16_f32 v32, v32, s0
	v_cndmask_b32_e32 v33, v102, v66, vcc
	v_mul_f32_e32 v33, v33, v34
	v_exp_f32_e32 v33, v33
	v_add_u32_e32 v34, -16, v68
	v_max_i32_e32 v34, v34, v35
	v_cvt_f32_u32_e32 v34, v34
	v_cmp_ne_u32_e32 vcc, 32, v77
	ds_write_b16 v67, v32 offset:1504
	v_sub_u32_e32 v35, 15, v68
	v_cndmask_b32_e32 v32, 2.0, v33, vcc
	v_mul_f32_e32 v33, 0x3db504f3, v39
	v_cmp_lt_i32_e32 vcc, 16, v68
	v_mul_f32_e32 v32, v33, v32
	v_cvt_pk_bf16_f32 v32, v32, s0
	v_cndmask_b32_e32 v33, v102, v66, vcc
	v_mul_f32_e32 v33, v33, v34
	v_exp_f32_e32 v33, v33
	v_add_u32_e32 v34, -15, v68
	v_max_i32_e32 v34, v34, v35
	v_cvt_f32_u32_e32 v34, v34
	v_cmp_ne_u32_e32 vcc, 32, v78
	ds_write_b16 v67, v32 offset:1648
	v_sub_u32_e32 v35, 14, v68
	v_cndmask_b32_e32 v32, 2.0, v33, vcc
	v_mul_f32_e32 v33, 0x3db504f3, v40
	v_cmp_lt_i32_e32 vcc, 15, v68
	v_mul_f32_e32 v32, v33, v32
	v_cvt_pk_bf16_f32 v32, v32, s0
	v_cndmask_b32_e32 v33, v102, v66, vcc
	v_mul_f32_e32 v33, v33, v34
	v_exp_f32_e32 v33, v33
	v_add_u32_e32 v34, -14, v68
	v_max_i32_e32 v34, v34, v35
	v_cvt_f32_u32_e32 v34, v34
	v_cmp_ne_u32_e32 vcc, 32, v79
	ds_write_b16 v67, v32 offset:2368
	v_sub_u32_e32 v35, 13, v68
	v_cndmask_b32_e32 v32, 2.0, v33, vcc
	v_mul_f32_e32 v33, 0x3db504f3, v41
	v_cmp_lt_i32_e32 vcc, 14, v68
	v_mul_f32_e32 v32, v33, v32
	v_cvt_pk_bf16_f32 v32, v32, s0
	v_cndmask_b32_e32 v33, v102, v66, vcc
	v_mul_f32_e32 v33, v33, v34
	v_exp_f32_e32 v33, v33
	v_add_u32_e32 v34, -13, v68
	v_max_i32_e32 v34, v34, v35
	v_cvt_f32_u32_e32 v34, v34
	v_cmp_ne_u32_e32 vcc, 32, v83
	ds_write_b16 v67, v32 offset:2512
	v_sub_u32_e32 v35, 8, v68
	v_cndmask_b32_e32 v32, 2.0, v33, vcc
	v_mul_f32_e32 v33, 0x3db504f3, v42
	v_cmp_lt_i32_e32 vcc, 13, v68
	v_mul_f32_e32 v32, v33, v32
	v_cvt_pk_bf16_f32 v32, v32, s0
	v_cndmask_b32_e32 v33, v102, v66, vcc
	v_mul_f32_e32 v33, v33, v34
	v_exp_f32_e32 v33, v33
	v_add_u32_e32 v34, -8, v68
	v_max_i32_e32 v34, v34, v35
	v_cvt_f32_u32_e32 v34, v34
	v_cmp_ne_u32_e32 vcc, 32, v84
	ds_write_b16 v67, v32 offset:2656
	v_sub_u32_e32 v35, 7, v68
	v_cndmask_b32_e32 v32, 2.0, v33, vcc
	v_mul_f32_e32 v33, 0x3db504f3, v43
	v_cmp_lt_i32_e32 vcc, 8, v68
	v_mul_f32_e32 v32, v33, v32
	v_cvt_pk_bf16_f32 v32, v32, s0
	v_cndmask_b32_e32 v33, v102, v66, vcc
	v_mul_f32_e32 v33, v33, v34
	v_exp_f32_e32 v33, v33
	v_add_u32_e32 v34, -7, v68
	v_max_i32_e32 v34, v34, v35
	v_cvt_f32_u32_e32 v34, v34
	v_cmp_ne_u32_e32 vcc, 32, v85
	ds_write_b16 v67, v32 offset:2800
	v_sub_u32_e32 v35, 6, v68
	v_cndmask_b32_e32 v32, 2.0, v33, vcc
	v_mul_f32_e32 v33, 0x3db504f3, v44
	v_cmp_lt_i32_e32 vcc, 7, v68
	v_mul_f32_e32 v32, v33, v32
	v_cvt_pk_bf16_f32 v32, v32, s0
	v_cndmask_b32_e32 v33, v102, v66, vcc
	v_mul_f32_e32 v33, v33, v34
	v_exp_f32_e32 v33, v33
	v_add_u32_e32 v34, -6, v68
	v_max_i32_e32 v34, v34, v35
	v_cvt_f32_u32_e32 v34, v34
	v_cmp_ne_u32_e32 vcc, 32, v86
	ds_write_b16 v67, v32 offset:3520
	v_sub_u32_e32 v35, 5, v68
	v_cndmask_b32_e32 v32, 2.0, v33, vcc
	v_mul_f32_e32 v33, 0x3db504f3, v45
	v_cmp_lt_i32_e32 vcc, 6, v68
	v_mul_f32_e32 v32, v33, v32
	v_cvt_pk_bf16_f32 v32, v32, s0
	v_cndmask_b32_e32 v33, v102, v66, vcc
	v_mul_f32_e32 v33, v33, v34
	v_exp_f32_e32 v33, v33
	v_add_u32_e32 v34, -5, v68
	v_max_i32_e32 v34, v34, v35
	v_cvt_f32_u32_e32 v34, v34
	v_cmp_ne_u32_e32 vcc, 32, v87
	ds_write_b16 v67, v32 offset:3664
	v_mfma_f32_32x32x16_bf16 v[16:31], v[124:127], v[132:135], v[16:31]
	v_cndmask_b32_e32 v32, 2.0, v33, vcc
	v_mul_f32_e32 v33, 0x3db504f3, v46
	v_cmp_lt_i32_e32 vcc, 5, v68
	v_mul_f32_e32 v32, v33, v32
	v_cvt_pk_bf16_f32 v32, v32, s0
	v_cndmask_b32_e32 v33, v102, v66, vcc
	v_mul_f32_e32 v33, v33, v34
	v_exp_f32_e32 v33, v33
	v_cmp_ne_u32_e32 vcc, 32, v88
	ds_write_b16 v67, v32 offset:3808
	v_mfma_f32_32x32x16_bf16 v[16:31], v[128:131], v[142:145], v[16:31]
	v_cndmask_b32_e32 v32, 2.0, v33, vcc
	v_mul_f32_e32 v33, 0x3db504f3, v47
	v_mul_f32_e32 v32, v33, v32
	v_add_u32_e32 v33, 32, v68
	v_sub_u32_e32 v34, 0, v33
	v_max_i32_e32 v34, v33, v34
	v_cvt_f32_u32_e32 v34, v34
	v_cvt_pk_bf16_f32 v32, v32, s0
	s_movk_i32 s0, 0xffe0
	v_cmp_lt_i32_e32 vcc, s0, v68
	ds_write_b16 v67, v32 offset:3952
	s_movk_i32 s0, 0xffdf
	v_cndmask_b32_e32 v35, v102, v66, vcc
	v_mul_f32_e32 v34, v35, v34
	v_exp_f32_e32 v34, v34
	v_cmp_ne_u32_e32 vcc, 0, v33
	v_add_u32_e32 v33, 33, v68
	v_mul_f32_e32 v16, 0x3db504f3, v16
	v_cndmask_b32_e32 v32, 2.0, v34, vcc
	v_sub_u32_e32 v34, 0, v33
	v_max_i32_e32 v34, v33, v34
	v_cvt_f32_u32_e32 v34, v34
	v_cmp_lt_i32_e32 vcc, s0, v68
	v_mul_f32_e32 v16, v16, v32
	v_cvt_pk_bf16_f32 v16, v16, s0
	v_cndmask_b32_e32 v32, v102, v66, vcc
	v_mul_f32_e32 v32, v32, v34
	v_exp_f32_e32 v32, v32
	v_cmp_ne_u32_e32 vcc, 0, v33
	ds_write_b16 v67, v16 offset:4608
	s_movk_i32 s0, 0xffde
	v_cndmask_b32_e32 v16, 2.0, v32, vcc
	v_add_u32_e32 v32, 34, v68
	v_sub_u32_e32 v34, 0, v32
	v_max_i32_e32 v34, v32, v34
	v_cvt_f32_u32_e32 v34, v34
	v_mul_f32_e32 v17, 0x3db504f3, v17
	v_cmp_lt_i32_e32 vcc, s0, v68
	v_mul_f32_e32 v16, v17, v16
	v_cvt_pk_bf16_f32 v16, v16, s0
	v_cndmask_b32_e32 v17, v102, v66, vcc
	v_mul_f32_e32 v17, v17, v34
	v_exp_f32_e32 v17, v17
	v_cmp_ne_u32_e32 vcc, 0, v32
	ds_write_b16 v67, v16 offset:4752
	s_movk_i32 s0, 0xffdd
	v_cndmask_b32_e32 v16, 2.0, v17, vcc
	v_mul_f32_e32 v17, 0x3db504f3, v18
	v_add_u32_e32 v18, 35, v68
	v_sub_u32_e32 v34, 0, v18
	v_max_i32_e32 v34, v18, v34
	v_cvt_f32_u32_e32 v34, v34
	v_cmp_lt_i32_e32 vcc, s0, v68
	v_mul_f32_e32 v16, v17, v16
	v_cvt_pk_bf16_f32 v16, v16, s0
	v_cndmask_b32_e32 v17, v102, v66, vcc
	v_mul_f32_e32 v17, v17, v34
	v_exp_f32_e32 v17, v17
	v_cmp_ne_u32_e32 vcc, 0, v18
	ds_write_b16 v67, v16 offset:4896
	s_movk_i32 s0, 0xffd8
	v_cndmask_b32_e32 v16, 2.0, v17, vcc
	v_mul_f32_e32 v17, 0x3db504f3, v19
	v_add_u32_e32 v19, 40, v68
	v_sub_u32_e32 v34, 0, v19
	v_max_i32_e32 v34, v19, v34
	v_cvt_f32_u32_e32 v34, v34
	v_cmp_lt_i32_e32 vcc, s0, v68
	v_mul_f32_e32 v16, v17, v16
	v_cvt_pk_bf16_f32 v16, v16, s0
	v_cndmask_b32_e32 v17, v102, v66, vcc
	v_mul_f32_e32 v17, v17, v34
	v_exp_f32_e32 v17, v17
	v_cmp_ne_u32_e32 vcc, 0, v19
	ds_write_b16 v67, v16 offset:5040
	s_movk_i32 s0, 0xffd7
	v_cndmask_b32_e32 v16, 2.0, v17, vcc
	v_mul_f32_e32 v17, 0x3db504f3, v20
	v_add_u32_e32 v20, 41, v68
	v_sub_u32_e32 v34, 0, v20
	v_max_i32_e32 v34, v20, v34
	v_cvt_f32_u32_e32 v34, v34
	v_cmp_lt_i32_e32 vcc, s0, v68
	v_mul_f32_e32 v16, v17, v16
	v_cvt_pk_bf16_f32 v16, v16, s0
	v_cndmask_b32_e32 v17, v102, v66, vcc
	v_mul_f32_e32 v17, v17, v34
	v_exp_f32_e32 v17, v17
	v_cmp_ne_u32_e32 vcc, 0, v20
	ds_write_b16 v67, v16 offset:5760
	s_movk_i32 s0, 0xffd6
	v_cndmask_b32_e32 v16, 2.0, v17, vcc
	v_mul_f32_e32 v17, 0x3db504f3, v21
	v_add_u32_e32 v21, 42, v68
	v_sub_u32_e32 v34, 0, v21
	v_max_i32_e32 v34, v21, v34
	v_cvt_f32_u32_e32 v34, v34
	v_cmp_lt_i32_e32 vcc, s0, v68
	v_mul_f32_e32 v16, v17, v16
	v_cvt_pk_bf16_f32 v16, v16, s0
	v_cndmask_b32_e32 v17, v102, v66, vcc
	v_mul_f32_e32 v17, v17, v34
	v_exp_f32_e32 v17, v17
	v_cmp_ne_u32_e32 vcc, 0, v21
	ds_write_b16 v67, v16 offset:5904
	s_movk_i32 s0, 0xffd5
	v_cndmask_b32_e32 v16, 2.0, v17, vcc
	v_mul_f32_e32 v17, 0x3db504f3, v22
	v_add_u32_e32 v22, 43, v68
	v_sub_u32_e32 v34, 0, v22
	v_max_i32_e32 v34, v22, v34
	v_cvt_f32_u32_e32 v34, v34
	v_cmp_lt_i32_e32 vcc, s0, v68
	v_mul_f32_e32 v16, v17, v16
	v_cvt_pk_bf16_f32 v16, v16, s0
	v_cndmask_b32_e32 v17, v102, v66, vcc
	v_mul_f32_e32 v17, v17, v34
	v_exp_f32_e32 v17, v17
	v_cmp_ne_u32_e32 vcc, 0, v22
	ds_write_b16 v67, v16 offset:6048
	s_movk_i32 s0, 0xffd0
	v_cndmask_b32_e32 v16, 2.0, v17, vcc
	v_mul_f32_e32 v17, 0x3db504f3, v23
	v_add_u32_e32 v23, 48, v68
	v_sub_u32_e32 v34, 0, v23
	v_max_i32_e32 v34, v23, v34
	v_cvt_f32_u32_e32 v34, v34
	v_cmp_lt_i32_e32 vcc, s0, v68
	v_mul_f32_e32 v16, v17, v16
	v_cvt_pk_bf16_f32 v16, v16, s0
	v_cndmask_b32_e32 v17, v102, v66, vcc
	v_mul_f32_e32 v17, v17, v34
	v_exp_f32_e32 v17, v17
	v_cmp_ne_u32_e32 vcc, 0, v23
	ds_write_b16 v67, v16 offset:6192
	s_movk_i32 s0, 0xffcf
	v_cndmask_b32_e32 v16, 2.0, v17, vcc
	v_mul_f32_e32 v17, 0x3db504f3, v24
	v_add_u32_e32 v24, 49, v68
	v_sub_u32_e32 v34, 0, v24
	v_max_i32_e32 v34, v24, v34
	v_cvt_f32_u32_e32 v34, v34
	v_cmp_lt_i32_e32 vcc, s0, v68
	v_mul_f32_e32 v16, v17, v16
	v_cvt_pk_bf16_f32 v16, v16, s0
	v_cndmask_b32_e32 v17, v102, v66, vcc
	v_mul_f32_e32 v17, v17, v34
	v_exp_f32_e32 v17, v17
	v_cmp_ne_u32_e32 vcc, 0, v24
	ds_write_b16 v67, v16 offset:6912
	s_movk_i32 s0, 0xffce
	v_cndmask_b32_e32 v16, 2.0, v17, vcc
	v_mul_f32_e32 v17, 0x3db504f3, v25
	v_add_u32_e32 v25, 50, v68
	v_sub_u32_e32 v34, 0, v25
	v_max_i32_e32 v34, v25, v34
	v_cvt_f32_u32_e32 v34, v34
	v_cmp_lt_i32_e32 vcc, s0, v68
	v_mul_f32_e32 v16, v17, v16
	v_cvt_pk_bf16_f32 v16, v16, s0
	v_cndmask_b32_e32 v17, v102, v66, vcc
	v_mul_f32_e32 v17, v17, v34
	v_exp_f32_e32 v17, v17
	v_cmp_ne_u32_e32 vcc, 0, v25
	ds_write_b16 v67, v16 offset:7056
	s_movk_i32 s0, 0xffcd
	v_cndmask_b32_e32 v16, 2.0, v17, vcc
	v_mul_f32_e32 v17, 0x3db504f3, v26
	v_add_u32_e32 v26, 51, v68
	v_sub_u32_e32 v34, 0, v26
	v_max_i32_e32 v34, v26, v34
	v_cvt_f32_u32_e32 v34, v34
	v_cmp_lt_i32_e32 vcc, s0, v68
	v_mul_f32_e32 v16, v17, v16
	v_cvt_pk_bf16_f32 v16, v16, s0
	v_cndmask_b32_e32 v17, v102, v66, vcc
	v_mul_f32_e32 v17, v17, v34
	v_exp_f32_e32 v17, v17
	v_cmp_ne_u32_e32 vcc, 0, v26
	ds_write_b16 v67, v16 offset:7200
	s_movk_i32 s0, 0xffc8
	v_cndmask_b32_e32 v16, 2.0, v17, vcc
	v_mul_f32_e32 v17, 0x3db504f3, v27
	v_add_u32_e32 v27, 56, v68
	v_sub_u32_e32 v34, 0, v27
	v_max_i32_e32 v34, v27, v34
	v_cvt_f32_u32_e32 v34, v34
	v_cmp_lt_i32_e32 vcc, s0, v68
	v_mul_f32_e32 v16, v17, v16
	v_cvt_pk_bf16_f32 v16, v16, s0
	v_cndmask_b32_e32 v17, v102, v66, vcc
	v_mul_f32_e32 v17, v17, v34
	v_exp_f32_e32 v17, v17
	v_cmp_ne_u32_e32 vcc, 0, v27
	ds_write_b16 v67, v16 offset:7344
	s_movk_i32 s0, 0xffc7
	v_cndmask_b32_e32 v16, 2.0, v17, vcc
	v_mul_f32_e32 v17, 0x3db504f3, v28
	v_add_u32_e32 v28, 57, v68
	v_sub_u32_e32 v34, 0, v28
	v_max_i32_e32 v34, v28, v34
	v_cvt_f32_u32_e32 v34, v34
	v_cmp_lt_i32_e32 vcc, s0, v68
	v_mul_f32_e32 v16, v17, v16
	v_cvt_pk_bf16_f32 v16, v16, s0
	v_cndmask_b32_e32 v17, v102, v66, vcc
	v_mul_f32_e32 v17, v17, v34
	v_exp_f32_e32 v17, v17
	v_cmp_ne_u32_e32 vcc, 0, v28
	ds_write_b16 v67, v16 offset:8064
	s_movk_i32 s0, 0xffc6
	v_cndmask_b32_e32 v16, 2.0, v17, vcc
	v_mul_f32_e32 v17, 0x3db504f3, v29
	v_add_u32_e32 v29, 58, v68
	v_sub_u32_e32 v34, 0, v29
	v_max_i32_e32 v34, v29, v34
	v_cvt_f32_u32_e32 v34, v34
	v_cmp_lt_i32_e32 vcc, s0, v68
	v_mfma_f32_32x32x16_bf16 v[0:15], v[124:127], v[146:149], v[0:15]
	v_mul_f32_e32 v16, v17, v16
	v_cndmask_b32_e32 v17, v102, v66, vcc
	v_mul_f32_e32 v17, v17, v34
	v_exp_f32_e32 v17, v17
	v_cvt_pk_bf16_f32 v16, v16, s0
	v_cmp_ne_u32_e32 vcc, 0, v29
	ds_write_b16 v67, v16 offset:8208
	v_mfma_f32_32x32x16_bf16 v[0:15], v[128:131], v[150:153], v[0:15]
	v_cndmask_b32_e32 v16, 2.0, v17, vcc
	v_mul_f32_e32 v17, 0x3db504f3, v30
	v_add_u32_e32 v30, 59, v68
	v_sub_u32_e32 v34, 0, v30
	v_max_i32_e32 v34, v30, v34
	v_cvt_f32_u32_e32 v34, v34
	s_movk_i32 s0, 0xffc5
	v_cmp_lt_i32_e32 vcc, s0, v68
	v_mul_f32_e32 v16, v17, v16
	s_nop 2
	v_mul_f32_e32 v0, 0x3db504f3, v0
	v_cndmask_b32_e32 v17, v102, v66, vcc
	v_mul_f32_e32 v17, v17, v34
	v_exp_f32_e32 v17, v17
	v_cvt_pk_bf16_f32 v16, v16, s0
	v_cmp_ne_u32_e32 vcc, 0, v30
	v_mul_f32_e32 v0, v0, v69
	ds_write_b16 v67, v16 offset:8352
	v_cndmask_b32_e32 v16, 2.0, v17, vcc
	v_cvt_pk_bf16_f32 v0, v0, s0
	v_cmp_ne_u32_e32 vcc, 32, v33
	ds_write_b16 v67, v0 offset:4672
	v_mul_f32_e32 v1, 0x3db504f3, v1
	v_cndmask_b32_e32 v0, 2.0, v48, vcc
	v_mul_f32_e32 v0, v1, v0
	v_cvt_pk_bf16_f32 v0, v0, s0
	v_cmp_ne_u32_e32 vcc, 32, v32
	ds_write_b16 v67, v0 offset:4816
	v_mul_f32_e32 v1, 0x3db504f3, v2
	v_cndmask_b32_e32 v0, 2.0, v49, vcc
	v_mul_f32_e32 v0, v1, v0
	v_cvt_pk_bf16_f32 v0, v0, s0
	v_cmp_ne_u32_e32 vcc, 32, v18
	ds_write_b16 v67, v0 offset:4960
	v_mul_f32_e32 v1, 0x3db504f3, v3
	v_cndmask_b32_e32 v0, 2.0, v50, vcc
	v_mul_f32_e32 v0, v1, v0
	v_cvt_pk_bf16_f32 v0, v0, s0
	v_cmp_ne_u32_e32 vcc, 32, v19
	ds_write_b16 v67, v0 offset:5104
	v_mul_f32_e32 v1, 0x3db504f3, v4
	v_cndmask_b32_e32 v0, 2.0, v51, vcc
	v_mul_f32_e32 v0, v1, v0
	v_cvt_pk_bf16_f32 v0, v0, s0
	v_cmp_ne_u32_e32 vcc, 32, v20
	ds_write_b16 v67, v0 offset:5824
	v_mul_f32_e32 v1, 0x3db504f3, v5
	v_cndmask_b32_e32 v0, 2.0, v52, vcc
	v_mul_f32_e32 v0, v1, v0
	v_cvt_pk_bf16_f32 v0, v0, s0
	v_cmp_ne_u32_e32 vcc, 32, v21
	ds_write_b16 v67, v0 offset:5968
	v_mul_f32_e32 v1, 0x3db504f3, v6
	v_cndmask_b32_e32 v0, 2.0, v53, vcc
	v_mul_f32_e32 v0, v1, v0
	v_cvt_pk_bf16_f32 v0, v0, s0
	v_cmp_ne_u32_e32 vcc, 32, v22
	ds_write_b16 v67, v0 offset:6112
	v_mul_f32_e32 v1, 0x3db504f3, v7
	v_cndmask_b32_e32 v0, 2.0, v54, vcc
	v_mul_f32_e32 v0, v1, v0
	v_cvt_pk_bf16_f32 v0, v0, s0
	v_cmp_ne_u32_e32 vcc, 32, v23
	ds_write_b16 v67, v0 offset:6256
	v_mul_f32_e32 v1, 0x3db504f3, v8
	v_cndmask_b32_e32 v0, 2.0, v55, vcc
	v_mul_f32_e32 v0, v1, v0
	v_cvt_pk_bf16_f32 v0, v0, s0
	v_cmp_ne_u32_e32 vcc, 32, v24
	ds_write_b16 v67, v0 offset:6976
	v_mul_f32_e32 v1, 0x3db504f3, v9
	v_cndmask_b32_e32 v0, 2.0, v56, vcc
	v_mul_f32_e32 v0, v1, v0
	v_cvt_pk_bf16_f32 v0, v0, s0
	v_cmp_ne_u32_e32 vcc, 32, v25
	ds_write_b16 v67, v0 offset:7120
	v_mul_f32_e32 v1, 0x3db504f3, v10
	v_cndmask_b32_e32 v0, 2.0, v57, vcc
	v_mul_f32_e32 v0, v1, v0
	v_cvt_pk_bf16_f32 v0, v0, s0
	v_cmp_ne_u32_e32 vcc, 32, v26
	ds_write_b16 v67, v0 offset:7264
	v_mul_f32_e32 v1, 0x3db504f3, v11
	v_cndmask_b32_e32 v0, 2.0, v58, vcc
	v_mul_f32_e32 v0, v1, v0
	v_cvt_pk_bf16_f32 v0, v0, s0
	v_cmp_ne_u32_e32 vcc, 32, v27
	ds_write_b16 v67, v0 offset:7408
	v_mul_f32_e32 v1, 0x3db504f3, v12
	v_cndmask_b32_e32 v0, 2.0, v59, vcc
	v_mul_f32_e32 v0, v1, v0
	v_cvt_pk_bf16_f32 v0, v0, s0
	v_cmp_ne_u32_e32 vcc, 32, v28
	ds_write_b16 v67, v0 offset:8128
	v_mul_f32_e32 v1, 0x3db504f3, v13
	v_cndmask_b32_e32 v0, 2.0, v60, vcc
	v_mul_f32_e32 v0, v1, v0
	v_cvt_pk_bf16_f32 v0, v0, s0
	v_cmp_ne_u32_e32 vcc, 32, v29
	ds_write_b16 v67, v0 offset:8272
	v_mul_f32_e32 v1, 0x3db504f3, v14
	v_cndmask_b32_e32 v0, 2.0, v61, vcc
	v_mul_f32_e32 v0, v1, v0
	v_cvt_pk_bf16_f32 v0, v0, s0
	v_cmp_ne_u32_e32 vcc, 32, v30
	ds_write_b16 v67, v0 offset:8416
	v_mul_f32_e32 v1, 0x3db504f3, v15
	v_cndmask_b32_e32 v0, 2.0, v62, vcc
	v_mul_f32_e32 v0, v1, v0
	v_cvt_pk_bf16_f32 v0, v0, s0
	ds_write_b16 v67, v0 offset:8560
	v_lshlrev_b32_e32 v0, 1, v64
	v_and_b32_e32 v32, 0x7e, v0
	v_mul_f32_e32 v17, 0x3db504f3, v31
	v_mul_u32_u24_e32 v0, 0xa00, v32
	v_mul_f32_e32 v16, v17, v16
	v_lshlrev_b32_e32 v0, 1, v0
	v_mov_b32_e32 v1, v137
	v_and_b32_e32 v33, 0x60, v65
	v_cvt_pk_bf16_f32 v16, v16, s0
	v_lshl_add_u64 v[0:1], s[40:41], 0, v[0:1]
	v_lshlrev_b32_e32 v2, 1, v33
	v_mov_b32_e32 v3, v137
	ds_write_b16 v67, v16 offset:8496
	v_lshl_add_u64 v[24:25], v[0:1], 0, v[2:3]
	s_movk_i32 s0, 0x1000
	v_add_co_u32_e32 v4, vcc, s0, v24
	global_load_dwordx4 v[0:3], v[24:25], off offset:2880
	s_nop 0
	v_addc_co_u32_e32 v5, vcc, 0, v25, vcc
	global_load_dwordx4 v[4:7], v[4:5], off offset:3904
	s_nop 0
	global_load_dwordx4 v[8:11], v[24:25], off offset:2896
	s_mov_b64 s[0:1], 0x1f40
	v_lshl_add_u64 v[28:29], v[24:25], 0, s[0:1]
	global_load_dwordx4 v[12:15], v[28:29], off offset:16
	global_load_dwordx4 v[16:19], v[24:25], off offset:2912
	global_load_dwordx4 v[20:23], v[28:29], off offset:32
	s_nop 0
	global_load_dwordx4 v[24:27], v[24:25], off offset:2928
	v_lshlrev_b32_e32 v30, 2, v64
	v_and_b32_e32 v34, 0x7c, v30
	global_load_dwordx4 v[28:31], v[28:29], off offset:48
	v_mov_b32_e32 v35, s83
	v_mov_b32_e32 v36, s82
	v_cmp_gt_u32_e32 vcc, 64, v32
	v_mul_u32_u24_e32 v33, 0x90, v33
	s_cselect_b64 s[0:1], -1, 0
	v_cndmask_b32_e32 v32, v35, v36, vcc
	v_add3_u32 v32, v32, v34, v33
	s_and_b64 s[34:35], s[0:1], exec
	s_cselect_b32 s38, s38, s23
	s_cselect_b32 s39, s4, 0x11c20000
	s_cmp_eq_u32 s38, 0
	s_cselect_b64 s[34:35], -1, 0
	s_lshl_b32 s22, s22, 3
	s_and_b32 s22, s22, 0xffffff00
	s_lshl_b32 s23, s23, 2
	s_and_b64 s[42:43], s[0:1], s[34:35]
	s_or_b32 s34, s22, s23
	s_addk_i32 s34, 0xfe00
	s_and_b32 s35, s76, -8
	s_add_u32 s22, s92, s39
	s_addc_u32 s23, s93, 0
	s_and_b64 vcc, exec, s[42:43]
	s_waitcnt vmcnt(7)
	v_lshlrev_b32_e32 v35, 16, v0
	v_and_b32_e32 v0, 0xffff0000, v0
	s_waitcnt vmcnt(6)
	v_lshlrev_b32_e32 v36, 16, v4
	v_and_b32_e32 v4, 0xffff0000, v4
	v_cvt_pk_bf16_f32 v35, v35, v36
	v_cvt_pk_bf16_f32 v0, v0, v4
	ds_write2_b32 v32, v35, v0 offset1:36
	v_lshlrev_b32_e32 v0, 16, v1
	v_lshlrev_b32_e32 v4, 16, v5
	v_cvt_pk_bf16_f32 v0, v0, v4
	v_and_b32_e32 v1, 0xffff0000, v1
	v_and_b32_e32 v4, 0xffff0000, v5
	v_cvt_pk_bf16_f32 v1, v1, v4
	ds_write2_b32 v32, v0, v1 offset0:72 offset1:108
	v_lshlrev_b32_e32 v0, 16, v2
	v_lshlrev_b32_e32 v1, 16, v6
	v_cvt_pk_bf16_f32 v0, v0, v1
	v_and_b32_e32 v1, 0xffff0000, v2
	v_and_b32_e32 v2, 0xffff0000, v6
	v_cvt_pk_bf16_f32 v1, v1, v2
	ds_write2_b32 v32, v0, v1 offset0:144 offset1:180
	v_lshlrev_b32_e32 v0, 16, v3
	v_lshlrev_b32_e32 v1, 16, v7
	v_cvt_pk_bf16_f32 v0, v0, v1
	v_and_b32_e32 v1, 0xffff0000, v3
	v_and_b32_e32 v2, 0xffff0000, v7
	v_cvt_pk_bf16_f32 v1, v1, v2
	ds_write2_b32 v32, v0, v1 offset0:216 offset1:252
	s_waitcnt vmcnt(5)
	v_lshlrev_b32_e32 v0, 16, v8
	s_waitcnt vmcnt(4)
	v_lshlrev_b32_e32 v1, 16, v12
	v_cvt_pk_bf16_f32 v0, v0, v1
	v_and_b32_e32 v1, 0xffff0000, v8
	v_and_b32_e32 v2, 0xffff0000, v12
	v_cvt_pk_bf16_f32 v1, v1, v2
	v_add_u32_e32 v2, 0x400, v32
	ds_write2_b32 v2, v0, v1 offset0:32 offset1:68
	v_lshlrev_b32_e32 v0, 16, v9
	v_lshlrev_b32_e32 v1, 16, v13
	v_cvt_pk_bf16_f32 v0, v0, v1
	v_and_b32_e32 v1, 0xffff0000, v9
	v_and_b32_e32 v3, 0xffff0000, v13
	v_cvt_pk_bf16_f32 v1, v1, v3
	ds_write2_b32 v2, v0, v1 offset0:104 offset1:140
	v_lshlrev_b32_e32 v0, 16, v10
	v_lshlrev_b32_e32 v1, 16, v14
	v_cvt_pk_bf16_f32 v0, v0, v1
	v_and_b32_e32 v1, 0xffff0000, v10
	v_and_b32_e32 v3, 0xffff0000, v14
	v_cvt_pk_bf16_f32 v1, v1, v3
	ds_write2_b32 v2, v0, v1 offset0:176 offset1:212
	v_lshlrev_b32_e32 v0, 16, v11
	v_lshlrev_b32_e32 v1, 16, v15
	v_cvt_pk_bf16_f32 v0, v0, v1
	v_and_b32_e32 v1, 0xffff0000, v11
	v_and_b32_e32 v2, 0xffff0000, v15
	v_cvt_pk_bf16_f32 v1, v1, v2
	v_add_u32_e32 v2, 0x600, v32
	ds_write2_b32 v2, v0, v1 offset0:120 offset1:156
	s_waitcnt vmcnt(3)
	v_lshlrev_b32_e32 v0, 16, v16
	s_waitcnt vmcnt(2)
	v_lshlrev_b32_e32 v1, 16, v20
	v_cvt_pk_bf16_f32 v0, v0, v1
	v_and_b32_e32 v1, 0xffff0000, v16
	v_and_b32_e32 v2, 0xffff0000, v20
	v_cvt_pk_bf16_f32 v1, v1, v2
	v_add_u32_e32 v2, 0x800, v32
	ds_write2_b32 v2, v0, v1 offset0:64 offset1:100
	v_lshlrev_b32_e32 v0, 16, v17
	v_lshlrev_b32_e32 v1, 16, v21
	v_cvt_pk_bf16_f32 v0, v0, v1
	v_and_b32_e32 v1, 0xffff0000, v17
	v_and_b32_e32 v3, 0xffff0000, v21
	v_cvt_pk_bf16_f32 v1, v1, v3
	ds_write2_b32 v2, v0, v1 offset0:136 offset1:172
	v_lshlrev_b32_e32 v0, 16, v18
	v_lshlrev_b32_e32 v1, 16, v22
	v_cvt_pk_bf16_f32 v0, v0, v1
	v_and_b32_e32 v1, 0xffff0000, v18
	v_and_b32_e32 v3, 0xffff0000, v22
	v_cvt_pk_bf16_f32 v1, v1, v3
	ds_write2_b32 v2, v0, v1 offset0:208 offset1:244
	v_lshlrev_b32_e32 v0, 16, v19
	v_lshlrev_b32_e32 v1, 16, v23
	v_cvt_pk_bf16_f32 v0, v0, v1
	v_and_b32_e32 v1, 0xffff0000, v19
	v_and_b32_e32 v2, 0xffff0000, v23
	v_cvt_pk_bf16_f32 v1, v1, v2
	v_add_u32_e32 v2, 0xc00, v32
	ds_write2_b32 v2, v0, v1 offset0:24 offset1:60
	s_waitcnt vmcnt(1)
	v_lshlrev_b32_e32 v0, 16, v24
	s_waitcnt vmcnt(0)
	v_lshlrev_b32_e32 v1, 16, v28
	v_cvt_pk_bf16_f32 v0, v0, v1
	v_and_b32_e32 v1, 0xffff0000, v24
	v_and_b32_e32 v3, 0xffff0000, v28
	v_cvt_pk_bf16_f32 v1, v1, v3
	ds_write2_b32 v2, v0, v1 offset0:96 offset1:132
	v_lshlrev_b32_e32 v0, 16, v25
	v_lshlrev_b32_e32 v1, 16, v29
	v_cvt_pk_bf16_f32 v0, v0, v1
	v_and_b32_e32 v1, 0xffff0000, v25
	v_and_b32_e32 v3, 0xffff0000, v29
	v_cvt_pk_bf16_f32 v1, v1, v3
	ds_write2_b32 v2, v0, v1 offset0:168 offset1:204
	v_lshlrev_b32_e32 v0, 16, v26
	v_lshlrev_b32_e32 v1, 16, v30
	v_cvt_pk_bf16_f32 v0, v0, v1
	v_and_b32_e32 v1, 0xffff0000, v26
	v_and_b32_e32 v2, 0xffff0000, v30
	v_cvt_pk_bf16_f32 v1, v1, v2
	v_add_u32_e32 v2, 0xe00, v32
	ds_write2_b32 v2, v0, v1 offset0:112 offset1:148
	v_lshlrev_b32_e32 v0, 16, v27
	v_lshlrev_b32_e32 v1, 16, v31
	v_cvt_pk_bf16_f32 v0, v0, v1
	v_and_b32_e32 v1, 0xffff0000, v27
	v_and_b32_e32 v2, 0xffff0000, v31
	v_cvt_pk_bf16_f32 v1, v1, v2
	v_add_u32_e32 v2, 0x1000, v32
	ds_write2_b32 v2, v0, v1 offset0:56 offset1:92
	s_waitcnt lgkmcnt(0)
	s_barrier
	ds_read_b128 v[0:3], v97
	ds_read_b128 v[4:7], v98 offset:36864
	ds_read_b128 v[68:71], v97 offset:32
	ds_read_b128 v[72:75], v98 offset:36896
	ds_read_b128 v[16:19], v98 offset:41472
	ds_read_b128 v[76:79], v98 offset:41504
	s_waitcnt lgkmcnt(4)
	v_mfma_f32_32x32x16_bf16 v[32:47], v[0:3], v[4:7], 0
	ds_read_b128 v[20:23], v97 offset:4608
	ds_read_b128 v[84:87], v97 offset:4640
	s_waitcnt lgkmcnt(3)
	v_mfma_f32_32x32x16_bf16 v[48:63], v[0:3], v[16:19], 0
	s_waitcnt lgkmcnt(1)
	v_mfma_f32_32x32x16_bf16 v[0:15], v[20:23], v[4:7], 0
	v_mfma_f32_32x32x16_bf16 v[16:31], v[20:23], v[16:19], 0
	v_mfma_f32_32x32x16_bf16 v[32:47], v[68:71], v[72:75], v[32:47]
	v_mfma_f32_32x32x16_bf16 v[48:63], v[68:71], v[76:79], v[48:63]
	s_waitcnt lgkmcnt(0)
	v_mfma_f32_32x32x16_bf16 v[0:15], v[84:87], v[72:75], v[0:15]
	v_mfma_f32_32x32x16_bf16 v[16:31], v[84:87], v[76:79], v[16:31]
	ds_read_b128 v[68:71], v97 offset:64
	ds_read_b128 v[72:75], v98 offset:36928
	ds_read_b128 v[76:79], v97 offset:96
	ds_read_b128 v[84:87], v98 offset:36960
	ds_read_b128 v[88:91], v98 offset:41536
	ds_read_b128 v[104:107], v98 offset:41568
	s_waitcnt lgkmcnt(4)
	v_mfma_f32_32x32x16_bf16 v[32:47], v[68:71], v[72:75], v[32:47]
	s_waitcnt lgkmcnt(1)
	v_mfma_f32_32x32x16_bf16 v[48:63], v[68:71], v[88:91], v[48:63]
	ds_read_b128 v[68:71], v97 offset:4672
	ds_read_b128 v[108:111], v97 offset:4704
	s_waitcnt lgkmcnt(1)
	v_mfma_f32_32x32x16_bf16 v[0:15], v[68:71], v[72:75], v[0:15]
	v_mfma_f32_32x32x16_bf16 v[16:31], v[68:71], v[88:91], v[16:31]
	v_mfma_f32_32x32x16_bf16 v[32:47], v[76:79], v[84:87], v[32:47]
	v_mfma_f32_32x32x16_bf16 v[48:63], v[76:79], v[104:107], v[48:63]
	s_waitcnt lgkmcnt(0)
	v_mfma_f32_32x32x16_bf16 v[0:15], v[108:111], v[84:87], v[0:15]
	ds_read_b128 v[68:71], v97 offset:18432
	ds_read_b128 v[72:75], v98 offset:55296
	ds_read_b128 v[76:79], v97 offset:18464
	ds_read_b128 v[84:87], v98 offset:55328
	v_mfma_f32_32x32x16_bf16 v[16:31], v[108:111], v[104:107], v[16:31]
	ds_read_b128 v[88:91], v98 offset:59904
	ds_read_b128 v[104:107], v98 offset:59936
	s_waitcnt lgkmcnt(4)
	v_mfma_f32_32x32x16_bf16 v[32:47], v[68:71], v[72:75], v[32:47]
	s_waitcnt lgkmcnt(1)
	v_mfma_f32_32x32x16_bf16 v[48:63], v[68:71], v[88:91], v[48:63]
	ds_read_b128 v[68:71], v97 offset:23040
	ds_read_b128 v[108:111], v97 offset:23072
	s_waitcnt lgkmcnt(1)
	v_mfma_f32_32x32x16_bf16 v[0:15], v[68:71], v[72:75], v[0:15]
	v_mfma_f32_32x32x16_bf16 v[16:31], v[68:71], v[88:91], v[16:31]
	v_mfma_f32_32x32x16_bf16 v[32:47], v[76:79], v[84:87], v[32:47]
	v_mfma_f32_32x32x16_bf16 v[48:63], v[76:79], v[104:107], v[48:63]
	s_waitcnt lgkmcnt(0)
	v_mfma_f32_32x32x16_bf16 v[0:15], v[108:111], v[84:87], v[0:15]
	ds_read_b128 v[68:71], v97 offset:18496
	ds_read_b128 v[72:75], v98 offset:55360
	ds_read_b128 v[76:79], v97 offset:18528
	ds_read_b128 v[84:87], v98 offset:55392
	v_mfma_f32_32x32x16_bf16 v[16:31], v[108:111], v[104:107], v[16:31]
	ds_read_b128 v[88:91], v98 offset:59968
	ds_read_b128 v[108:111], v98 offset:60000
	v_or_b32_e32 v105, 32, v101
	v_or_b32_e32 v106, 64, v101
	v_or_b32_e32 v104, 0x60, v101
	v_add_u32_e32 v107, s24, v82
	s_waitcnt lgkmcnt(4)
	v_mfma_f32_32x32x16_bf16 v[32:47], v[68:71], v[72:75], v[32:47]
	s_waitcnt lgkmcnt(1)
	v_mfma_f32_32x32x16_bf16 v[48:63], v[68:71], v[88:91], v[48:63]
	ds_read_b128 v[68:71], v97 offset:23104
	ds_read_b128 v[112:115], v97 offset:23136
	s_waitcnt lgkmcnt(0)
	s_barrier
	v_mfma_f32_32x32x16_bf16 v[0:15], v[68:71], v[72:75], v[0:15]
	v_mfma_f32_32x32x16_bf16 v[16:31], v[68:71], v[88:91], v[16:31]
	v_lshlrev_b32_e32 v90, 8, v101
	v_lshlrev_b32_e32 v88, 8, v105
	v_mfma_f32_32x32x16_bf16 v[32:47], v[76:79], v[84:87], v[32:47]
	v_mfma_f32_32x32x16_bf16 v[48:63], v[76:79], v[108:111], v[48:63]
	v_mfma_f32_32x32x16_bf16 v[0:15], v[112:115], v[84:87], v[0:15]
	v_lshlrev_b32_e32 v86, 8, v106
	v_lshlrev_b32_e32 v84, 8, v104
	v_mfma_f32_32x32x16_bf16 v[16:31], v[112:115], v[108:111], v[16:31]
	s_cbranch_vccnz .LBB0_500
	v_mov_b32_e32 v83, v137
	v_lshl_add_u64 v[64:65], s[40:41], 0, v[82:83]
	v_lshl_add_u64 v[70:71], v[64:65], 0, v[80:81]
	v_lshl_add_u64 v[154:155], v[70:71], 0, s[8:9]
	v_lshl_add_u64 v[156:157], v[70:71], 0, s[10:11]
	v_lshl_add_u64 v[158:159], v[70:71], 0, s[12:13]
	global_load_dwordx4 v[116:119], v[70:71], off offset:832
	global_load_dwordx4 v[120:123], v[154:155], off offset:832
	global_load_dwordx4 v[124:127], v[156:157], off offset:832
	global_load_dwordx4 v[142:145], v[158:159], off offset:832
	global_load_dwordx4 v[146:149], v[70:71], off offset:960
	global_load_dwordx4 v[150:153], v[154:155], off offset:960
	global_load_dwordx4 v[160:163], v[156:157], off offset:960
	global_load_dwordx4 v[164:167], v[158:159], off offset:960
	v_add_u32_e32 v64, 1, v101
	v_cvt_f32_ubyte0_e32 v64, v64
	v_mul_f32_e32 v64, v66, v64
	v_exp_f32_e32 v68, v64
	v_mad_u32_u24 v67, v105, s5, v107
	s_and_b64 s[42:43], s[0:1], exec
	s_cselect_b32 s39, s35, s34
	s_or_b32 s42, s39, s78
	s_ashr_i32 s43, s42, 31
	s_lshl_b64 s[42:43], s[42:43], 15
	s_add_u32 s42, s22, s42
	s_addc_u32 s43, s23, s43
	v_mov_b32_e32 v91, v137
	v_mov_b32_e32 v89, v137
	v_mov_b32_e32 v87, v137
	v_mov_b32_e32 v85, v137
	s_mov_b64 s[6:7], 0x28000
	s_movk_i32 s4, 0x90
	s_waitcnt vmcnt(7)
	v_mov_b32_e32 v72, v116
	v_mov_b32_e32 v73, v117
	v_mov_b32_e32 v74, v118
	v_mov_b32_e32 v75, v119
	v_lshlrev_b32_e32 v64, 16, v72
	v_and_b32_e32 v65, 0xffff0000, v72
	v_pk_mul_f32 v[64:65], v[68:69], v[64:65] op_sel_hi:[0,1]
	v_cvt_pk_bf16_f32 v72, v64, v65
	v_lshlrev_b32_e32 v64, 16, v73
	v_and_b32_e32 v65, 0xffff0000, v73
	v_pk_mul_f32 v[64:65], v[68:69], v[64:65] op_sel_hi:[0,1]
	v_cvt_pk_bf16_f32 v73, v64, v65
	v_lshlrev_b32_e32 v64, 16, v74
	v_and_b32_e32 v65, 0xffff0000, v74
	v_pk_mul_f32 v[64:65], v[68:69], v[64:65] op_sel_hi:[0,1]
	v_cvt_pk_bf16_f32 v74, v64, v65
	v_lshlrev_b32_e32 v64, 16, v75
	v_and_b32_e32 v65, 0xffff0000, v75
	v_pk_mul_f32 v[64:65], v[68:69], v[64:65] op_sel_hi:[0,1]
	v_cvt_pk_bf16_f32 v75, v64, v65
	v_add_u32_e32 v69, v107, v103
	ds_write_b128 v69, v[72:75]
	v_lshl_add_u64 v[74:75], v[70:71], 0, s[8:9]
	v_add_u32_e32 v64, 33, v101
	v_cvt_f32_ubyte0_e32 v64, v64
	v_mul_f32_e32 v64, v66, v64
	v_exp_f32_e32 v72, v64
	s_mov_b64 s[8:9], 0x50000
	s_waitcnt vmcnt(6)
	v_mov_b32_e32 v76, v120
	v_mov_b32_e32 v77, v121
	v_mov_b32_e32 v78, v122
	v_mov_b32_e32 v79, v123
	v_lshlrev_b32_e32 v64, 16, v76
	v_and_b32_e32 v65, 0xffff0000, v76
	v_pk_mul_f32 v[64:65], v[72:73], v[64:65] op_sel_hi:[0,1]
	v_cvt_pk_bf16_f32 v76, v64, v65
	v_lshlrev_b32_e32 v64, 16, v77
	v_and_b32_e32 v65, 0xffff0000, v77
	v_pk_mul_f32 v[64:65], v[72:73], v[64:65] op_sel_hi:[0,1]
	v_cvt_pk_bf16_f32 v77, v64, v65
	v_lshlrev_b32_e32 v64, 16, v78
	v_and_b32_e32 v65, 0xffff0000, v78
	v_pk_mul_f32 v[64:65], v[72:73], v[64:65] op_sel_hi:[0,1]
	v_cvt_pk_bf16_f32 v78, v64, v65
	v_lshlrev_b32_e32 v64, 16, v79
	v_and_b32_e32 v65, 0xffff0000, v79
	v_pk_mul_f32 v[64:65], v[72:73], v[64:65] op_sel_hi:[0,1]
	v_cvt_pk_bf16_f32 v79, v64, v65
	ds_write_b128 v67, v[76:79]
	v_lshl_add_u64 v[78:79], v[70:71], 0, s[10:11]
	v_add_u32_e32 v64, 0x41, v101
	v_cvt_f32_ubyte0_e32 v64, v64
	v_mul_f32_e32 v64, v66, v64
	v_exp_f32_e32 v76, v64
	v_add_u32_e32 v73, 0x61, v101
	v_cvt_f32_ubyte0_e32 v73, v73
	v_mul_f32_e32 v66, v66, v73
	v_exp_f32_e32 v66, v66
	s_mov_b64 s[10:11], 0x78000
	s_waitcnt vmcnt(5)
	v_mov_b32_e32 v108, v124
	v_mov_b32_e32 v109, v125
	v_mov_b32_e32 v110, v126
	v_mov_b32_e32 v111, v127
	v_lshlrev_b32_e32 v64, 16, v108
	v_and_b32_e32 v65, 0xffff0000, v108
	v_pk_mul_f32 v[64:65], v[76:77], v[64:65] op_sel_hi:[0,1]
	v_cvt_pk_bf16_f32 v108, v64, v65
	v_lshlrev_b32_e32 v64, 16, v109
	v_and_b32_e32 v65, 0xffff0000, v109
	v_pk_mul_f32 v[64:65], v[76:77], v[64:65] op_sel_hi:[0,1]
	v_cvt_pk_bf16_f32 v109, v64, v65
	v_lshlrev_b32_e32 v64, 16, v110
	v_and_b32_e32 v65, 0xffff0000, v110
	v_pk_mul_f32 v[64:65], v[76:77], v[64:65] op_sel_hi:[0,1]
	v_cvt_pk_bf16_f32 v110, v64, v65
	v_lshlrev_b32_e32 v64, 16, v111
	v_and_b32_e32 v65, 0xffff0000, v111
	v_pk_mul_f32 v[64:65], v[76:77], v[64:65] op_sel_hi:[0,1]
	v_cvt_pk_bf16_f32 v111, v64, v65
	v_lshl_add_u64 v[64:65], v[70:71], 0, s[12:13]
	ds_write_b128 v67, v[108:111] offset:4608
	s_waitcnt vmcnt(4)
	v_mov_b32_e32 v108, v142
	v_mov_b32_e32 v109, v143
	v_mov_b32_e32 v110, v144
	v_mov_b32_e32 v111, v145
	v_lshlrev_b32_e32 v112, 16, v108
	v_and_b32_e32 v113, 0xffff0000, v108
	v_pk_mul_f32 v[112:113], v[66:67], v[112:113] op_sel_hi:[0,1]
	v_cvt_pk_bf16_f32 v108, v112, v113
	v_lshlrev_b32_e32 v112, 16, v109
	v_and_b32_e32 v113, 0xffff0000, v109
	v_pk_mul_f32 v[112:113], v[66:67], v[112:113] op_sel_hi:[0,1]
	v_cvt_pk_bf16_f32 v109, v112, v113
	v_lshlrev_b32_e32 v112, 16, v110
	v_and_b32_e32 v113, 0xffff0000, v110
	v_pk_mul_f32 v[112:113], v[66:67], v[112:113] op_sel_hi:[0,1]
	v_cvt_pk_bf16_f32 v110, v112, v113
	v_lshlrev_b32_e32 v112, 16, v111
	v_and_b32_e32 v113, 0xffff0000, v111
	v_pk_mul_f32 v[112:113], v[66:67], v[112:113] op_sel_hi:[0,1]
	v_cvt_pk_bf16_f32 v111, v112, v113
	ds_write_b128 v67, v[108:111] offset:9216
	s_waitcnt vmcnt(3)
	v_mov_b32_e32 v108, v146
	v_mov_b32_e32 v109, v147
	v_mov_b32_e32 v110, v148
	v_mov_b32_e32 v111, v149
	v_lshlrev_b32_e32 v70, 16, v108
	v_and_b32_e32 v71, 0xffff0000, v108
	v_pk_mul_f32 v[70:71], v[68:69], v[70:71] op_sel_hi:[0,1]
	v_cvt_pk_bf16_f32 v108, v70, v71
	v_lshlrev_b32_e32 v70, 16, v109
	v_and_b32_e32 v71, 0xffff0000, v109
	v_pk_mul_f32 v[70:71], v[68:69], v[70:71] op_sel_hi:[0,1]
	v_cvt_pk_bf16_f32 v109, v70, v71
	v_lshlrev_b32_e32 v70, 16, v110
	v_and_b32_e32 v71, 0xffff0000, v110
	v_pk_mul_f32 v[70:71], v[68:69], v[70:71] op_sel_hi:[0,1]
	v_cvt_pk_bf16_f32 v110, v70, v71
	v_lshlrev_b32_e32 v70, 16, v111
	v_and_b32_e32 v71, 0xffff0000, v111
	v_pk_mul_f32 v[70:71], v[68:69], v[70:71] op_sel_hi:[0,1]
	v_cvt_pk_bf16_f32 v111, v70, v71
	ds_write_b128 v69, v[108:111] offset:18432
	s_waitcnt vmcnt(2)
	v_mov_b32_e32 v68, v150
	v_mov_b32_e32 v69, v151
	v_mov_b32_e32 v70, v152
	v_mov_b32_e32 v71, v153
	v_lshlrev_b32_e32 v74, 16, v68
	v_and_b32_e32 v75, 0xffff0000, v68
	v_pk_mul_f32 v[74:75], v[72:73], v[74:75] op_sel_hi:[0,1]
	v_cvt_pk_bf16_f32 v68, v74, v75
	v_lshlrev_b32_e32 v74, 16, v69
	v_and_b32_e32 v75, 0xffff0000, v69
	v_pk_mul_f32 v[74:75], v[72:73], v[74:75] op_sel_hi:[0,1]
	v_cvt_pk_bf16_f32 v69, v74, v75
	v_lshlrev_b32_e32 v74, 16, v70
	v_and_b32_e32 v75, 0xffff0000, v70
	v_pk_mul_f32 v[74:75], v[72:73], v[74:75] op_sel_hi:[0,1]
	v_cvt_pk_bf16_f32 v70, v74, v75
	v_lshlrev_b32_e32 v74, 16, v71
	v_and_b32_e32 v75, 0xffff0000, v71
	v_pk_mul_f32 v[72:73], v[72:73], v[74:75] op_sel_hi:[0,1]
	v_cvt_pk_bf16_f32 v71, v72, v73
	ds_write_b128 v67, v[68:71] offset:18432
	s_waitcnt vmcnt(1)
	v_mov_b32_e32 v68, v160
	v_mov_b32_e32 v69, v161
	v_mov_b32_e32 v70, v162
	v_mov_b32_e32 v71, v163
	v_lshlrev_b32_e32 v72, 16, v68
	v_and_b32_e32 v73, 0xffff0000, v68
	v_pk_mul_f32 v[72:73], v[76:77], v[72:73] op_sel_hi:[0,1]
	v_cvt_pk_bf16_f32 v68, v72, v73
	v_lshlrev_b32_e32 v72, 16, v69
	v_and_b32_e32 v73, 0xffff0000, v69
	v_pk_mul_f32 v[72:73], v[76:77], v[72:73] op_sel_hi:[0,1]
	v_cvt_pk_bf16_f32 v69, v72, v73
	v_lshlrev_b32_e32 v72, 16, v70
	v_and_b32_e32 v73, 0xffff0000, v70
	v_pk_mul_f32 v[72:73], v[76:77], v[72:73] op_sel_hi:[0,1]
	v_cvt_pk_bf16_f32 v70, v72, v73
	v_lshlrev_b32_e32 v72, 16, v71
	v_and_b32_e32 v73, 0xffff0000, v71
	v_pk_mul_f32 v[72:73], v[76:77], v[72:73] op_sel_hi:[0,1]
	v_cvt_pk_bf16_f32 v71, v72, v73
	ds_write_b128 v67, v[68:71] offset:23040
	v_lshl_add_u64 v[76:77], s[42:43], 0, v[136:137]
	v_lshl_add_u64 v[108:109], v[76:77], 0, v[90:91]
	v_lshl_add_u64 v[110:111], v[76:77], 0, v[88:89]
	v_lshl_add_u64 v[112:113], v[76:77], 0, v[86:87]
	global_load_dwordx4 v[72:75], v[112:113], off
	v_lshl_add_u64 v[114:115], v[76:77], 0, v[84:85]
	global_load_dwordx4 v[76:79], v[114:115], off
	s_waitcnt vmcnt(2)
	v_mov_b32_e32 v68, v164
	v_mov_b32_e32 v69, v165
	v_mov_b32_e32 v70, v166
	v_mov_b32_e32 v71, v167
	v_lshlrev_b32_e32 v64, 16, v68
	v_and_b32_e32 v65, 0xffff0000, v68
	v_pk_mul_f32 v[64:65], v[66:67], v[64:65] op_sel_hi:[0,1]
	v_cvt_pk_bf16_f32 v68, v64, v65
	v_lshlrev_b32_e32 v64, 16, v69
	v_and_b32_e32 v65, 0xffff0000, v69
	v_pk_mul_f32 v[64:65], v[66:67], v[64:65] op_sel_hi:[0,1]
	v_cvt_pk_bf16_f32 v69, v64, v65
	v_lshlrev_b32_e32 v64, 16, v70
	v_and_b32_e32 v65, 0xffff0000, v70
	v_pk_mul_f32 v[64:65], v[66:67], v[64:65] op_sel_hi:[0,1]
	v_cvt_pk_bf16_f32 v70, v64, v65
	v_lshlrev_b32_e32 v64, 16, v71
	v_and_b32_e32 v65, 0xffff0000, v71
	v_pk_mul_f32 v[64:65], v[66:67], v[64:65] op_sel_hi:[0,1]
	v_cvt_pk_bf16_f32 v71, v64, v65
	ds_write_b128 v67, v[68:71] offset:27648
	global_load_dwordx4 v[64:67], v[108:109], off
	global_load_dwordx4 v[68:71], v[110:111], off
	s_waitcnt vmcnt(1)
	ds_write_b128 v99, v[64:67] offset:36864
	s_waitcnt vmcnt(0)
	ds_write_b128 v99, v[68:71] offset:41472
	ds_write_b128 v99, v[72:75] offset:46080
	ds_write_b128 v99, v[76:79] offset:50688
	global_load_dwordx4 v[64:67], v[108:109], off offset:128
	global_load_dwordx4 v[68:71], v[110:111], off offset:128
	global_load_dwordx4 v[72:75], v[112:113], off offset:128
	global_load_dwordx4 v[76:79], v[114:115], off offset:128
	s_waitcnt vmcnt(3)
	ds_write_b128 v99, v[64:67] offset:55296
	s_waitcnt vmcnt(2)
	ds_write_b128 v99, v[68:71] offset:59904
	s_waitcnt vmcnt(1)
	ds_write_b128 v99, v[72:75] offset:64512
	s_waitcnt vmcnt(0)
	ds_write_b128 v100, v[76:79] offset:13824
	s_waitcnt lgkmcnt(0)
	s_barrier
	ds_read_b128 v[64:67], v97 offset:4608
	ds_read_b128 v[68:71], v98 offset:41472
	ds_read_b128 v[72:75], v97
	ds_read_b128 v[76:79], v97 offset:32
	ds_read_b128 v[108:111], v97 offset:4640
	ds_read_b128 v[112:115], v98 offset:36864
	ds_read_b128 v[116:119], v98 offset:36896
	ds_read_b128 v[120:123], v98 offset:41504
	ds_read_b128 v[124:127], v97 offset:64
	ds_read_b128 v[128:131], v97 offset:4672
	ds_read_b128 v[132:135], v98 offset:36928
	ds_read_b128 v[142:145], v98 offset:41536
	ds_read_b128 v[146:149], v97 offset:96
	ds_read_b128 v[150:153], v97 offset:4704
	ds_read_b128 v[154:157], v98 offset:36960
	ds_read_b128 v[158:161], v98 offset:41568
	s_waitcnt lgkmcnt(10)
	v_mfma_f32_32x32x16_bf16 v[32:47], v[72:75], v[112:115], v[32:47]
	v_mfma_f32_32x32x16_bf16 v[48:63], v[72:75], v[68:71], v[48:63]
	v_mfma_f32_32x32x16_bf16 v[0:15], v[64:67], v[112:115], v[0:15]
	v_mfma_f32_32x32x16_bf16 v[16:31], v[64:67], v[68:71], v[16:31]
	s_waitcnt lgkmcnt(9)
	v_mfma_f32_32x32x16_bf16 v[32:47], v[76:79], v[116:119], v[32:47]
	s_waitcnt lgkmcnt(8)
	v_mfma_f32_32x32x16_bf16 v[48:63], v[76:79], v[120:123], v[48:63]
	v_mfma_f32_32x32x16_bf16 v[0:15], v[108:111], v[116:119], v[0:15]
	v_mfma_f32_32x32x16_bf16 v[16:31], v[108:111], v[120:123], v[16:31]
	s_waitcnt lgkmcnt(5)
	v_mfma_f32_32x32x16_bf16 v[32:47], v[124:127], v[132:135], v[32:47]
	s_waitcnt lgkmcnt(4)
	v_mfma_f32_32x32x16_bf16 v[48:63], v[124:127], v[142:145], v[48:63]
	v_mfma_f32_32x32x16_bf16 v[0:15], v[128:131], v[132:135], v[0:15]
	v_mfma_f32_32x32x16_bf16 v[16:31], v[128:131], v[142:145], v[16:31]
	s_waitcnt lgkmcnt(1)
	v_mfma_f32_32x32x16_bf16 v[32:47], v[146:149], v[154:157], v[32:47]
	s_waitcnt lgkmcnt(0)
	v_mfma_f32_32x32x16_bf16 v[48:63], v[146:149], v[158:161], v[48:63]
	v_mfma_f32_32x32x16_bf16 v[0:15], v[150:153], v[154:157], v[0:15]
	v_mfma_f32_32x32x16_bf16 v[16:31], v[150:153], v[158:161], v[16:31]
	ds_read_b128 v[64:67], v97 offset:23040
	ds_read_b128 v[68:71], v98 offset:59904
	ds_read_b128 v[72:75], v97 offset:18432
	ds_read_b128 v[76:79], v97 offset:18464
	ds_read_b128 v[108:111], v97 offset:23072
	ds_read_b128 v[112:115], v98 offset:55296
	ds_read_b128 v[116:119], v98 offset:55328
	ds_read_b128 v[120:123], v98 offset:59936
	ds_read_b128 v[124:127], v97 offset:18496
	ds_read_b128 v[128:131], v97 offset:23104
	ds_read_b128 v[132:135], v98 offset:55360
	ds_read_b128 v[142:145], v98 offset:59968
	ds_read_b128 v[146:149], v97 offset:18528
	ds_read_b128 v[150:153], v97 offset:23136
	ds_read_b128 v[154:157], v98 offset:55392
	ds_read_b128 v[158:161], v98 offset:60000
	s_waitcnt lgkmcnt(0)
	s_barrier
	v_mfma_f32_32x32x16_bf16 v[32:47], v[72:75], v[112:115], v[32:47]
	v_mfma_f32_32x32x16_bf16 v[48:63], v[72:75], v[68:71], v[48:63]
	v_mfma_f32_32x32x16_bf16 v[0:15], v[64:67], v[112:115], v[0:15]
	v_mfma_f32_32x32x16_bf16 v[16:31], v[64:67], v[68:71], v[16:31]
	v_mfma_f32_32x32x16_bf16 v[32:47], v[76:79], v[116:119], v[32:47]
	v_mfma_f32_32x32x16_bf16 v[48:63], v[76:79], v[120:123], v[48:63]
	v_mfma_f32_32x32x16_bf16 v[0:15], v[108:111], v[116:119], v[0:15]
	v_mfma_f32_32x32x16_bf16 v[16:31], v[108:111], v[120:123], v[16:31]
	v_mfma_f32_32x32x16_bf16 v[32:47], v[124:127], v[132:135], v[32:47]
	v_mfma_f32_32x32x16_bf16 v[48:63], v[124:127], v[142:145], v[48:63]
	v_mfma_f32_32x32x16_bf16 v[0:15], v[128:131], v[132:135], v[0:15]
	v_mfma_f32_32x32x16_bf16 v[16:31], v[128:131], v[142:145], v[16:31]
	v_mfma_f32_32x32x16_bf16 v[32:47], v[146:149], v[154:157], v[32:47]
	v_mfma_f32_32x32x16_bf16 v[48:63], v[146:149], v[158:161], v[48:63]
	v_mfma_f32_32x32x16_bf16 v[0:15], v[150:153], v[154:157], v[0:15]
	v_mfma_f32_32x32x16_bf16 v[16:31], v[150:153], v[158:161], v[16:31]
	s_branch .LBB0_501

.LBB0_631:
	s_and_b64 vcc, exec, s[0:1]
	s_cbranch_vccz .LBB0_704
	s_addk_i32 s76, 0x200
	s_ashr_i32 s22, s76, 2
	s_lshl_b32 s44, s22, 7
	s_cmp_lt_i32 s22, 64
	s_cselect_b64 s[40:41], -1, 0
	s_and_b32 s23, s22, 31
	s_mul_i32 s0, s22, 0xa0000
	v_mov_b32_e32 v64, v139
	s_mul_hi_i32 s1, s44, 0x1400
	s_add_u32 s0, s92, s0
	s_addc_u32 s1, s93, s1
	s_lshl_b32 s34, s81, 1
	v_lshlrev_b32_e32 v0, 3, v64
	s_add_u32 s42, s0, s34
	v_and_b32_e32 v0, 56, v0
	v_bfe_u32 v102, v64, 3, 5
	s_addc_u32 s43, s1, 0
	v_lshlrev_b32_e32 v136, 1, v0
	v_mul_u32_u24_e32 v2, 0xa00, v102
	v_lshl_add_u64 v[0:1], s[42:43], 0, v[136:137]
	v_lshlrev_b32_e32 v80, 1, v2
	v_mov_b32_e32 v81, v137
	v_lshl_add_u64 v[24:25], v[0:1], 0, v[80:81]
	s_mov_b64 s[8:9], 0x28000
	s_mov_b64 s[10:11], 0x50000
	s_mov_b64 s[12:13], 0x78000
	v_lshl_add_u64 v[52:53], v[24:25], 0, s[8:9]
	v_lshl_add_u64 v[56:57], v[24:25], 0, s[10:11]
	v_lshl_add_u64 v[60:61], v[24:25], 0, s[12:13]
	global_load_dwordx4 v[0:3], v[52:53], off offset:832
	global_load_dwordx4 v[4:7], v[24:25], off offset:832
	global_load_dwordx4 v[8:11], v[24:25], off offset:960
	global_load_dwordx4 v[12:15], v[24:25], off offset:1856
	global_load_dwordx4 v[16:19], v[24:25], off offset:1984
	global_load_dwordx4 v[20:23], v[56:57], off offset:832
	s_nop 0
	global_load_dwordx4 v[24:27], v[60:61], off offset:832
	global_load_dwordx4 v[28:31], v[52:53], off offset:960
	global_load_dwordx4 v[32:35], v[56:57], off offset:960
	global_load_dwordx4 v[36:39], v[60:61], off offset:960
	global_load_dwordx4 v[40:43], v[52:53], off offset:1856
	global_load_dwordx4 v[44:47], v[56:57], off offset:1856
	global_load_dwordx4 v[48:51], v[60:61], off offset:1856
	s_nop 0
	global_load_dwordx4 v[52:55], v[52:53], off offset:1984
	s_nop 0
	global_load_dwordx4 v[56:59], v[56:57], off offset:1984
	s_nop 0
	global_load_dwordx4 v[60:63], v[60:61], off offset:1984
	s_nop 0
	global_load_dword v78, v137, s[2:3]
	global_load_dword v79, v137, s[2:3] offset:16
	v_lshrrev_b32_e32 v65, 1, v64
	v_and_b32_e32 v92, 31, v64
	v_and_b32_e32 v95, 64, v65
	v_mov_b32_e32 v83, s24
	v_lshlrev_b32_e32 v66, 4, v64
	v_or_b32_e32 v67, v95, v92
	s_movk_i32 s5, 0x90
	v_and_b32_e32 v82, 0x70, v66
	v_mul_u32_u24_e32 v103, 0x90, v102
	v_and_b32_e32 v66, 16, v65
	v_mad_u32_u24 v67, v67, s5, v83
	v_add3_u32 v99, s24, v82, v103
	v_add_u32_e32 v97, v67, v66
	v_add_u32_e32 v100, 0xd800, v99
	v_bfe_u32 v96, v64, 6, 1
	v_lshlrev_b32_e32 v93, 6, v96
	v_or_b32_e32 v94, v93, v92
	v_lshrrev_b32_e32 v128, 3, v64
	v_and_or_b32 v95, v128, 4, v95
	v_cmp_eq_u32_e32 vcc, 0, v96
	s_and_b32 s2, s22, 1
	s_waitcnt vmcnt(16)
	ds_write_b128 v99, v[4:7]
	s_waitcnt vmcnt(15)
	ds_write_b128 v99, v[8:11] offset:18432
	s_waitcnt vmcnt(14)
	ds_write_b128 v99, v[12:15] offset:36864
	s_waitcnt vmcnt(13)
	ds_write_b128 v99, v[16:19] offset:55296
	ds_write_b128 v99, v[0:3] offset:4608
	s_waitcnt vmcnt(12)
	ds_write_b128 v99, v[20:23] offset:9216
	s_waitcnt vmcnt(11)
	ds_write_b128 v99, v[24:27] offset:13824
	s_waitcnt vmcnt(10)
	ds_write_b128 v99, v[28:31] offset:23040
	s_waitcnt vmcnt(9)
	ds_write_b128 v99, v[32:35] offset:27648
	s_waitcnt vmcnt(8)
	ds_write_b128 v99, v[36:39] offset:32256
	s_waitcnt vmcnt(7)
	ds_write_b128 v99, v[40:43] offset:41472
	s_waitcnt vmcnt(6)
	ds_write_b128 v99, v[44:47] offset:46080
	s_waitcnt vmcnt(5)
	ds_write_b128 v99, v[48:51] offset:50688
	s_waitcnt vmcnt(4)
	ds_write_b128 v99, v[52:55] offset:59904
	s_waitcnt vmcnt(3)
	ds_write_b128 v99, v[56:59] offset:64512
	s_waitcnt vmcnt(2)
	ds_write_b128 v100, v[60:63] offset:13824
	s_waitcnt lgkmcnt(0)
	s_barrier
	ds_read_b128 v[0:3], v97
	v_mad_u32_u24 v4, v94, s5, v83
	v_add_u32_e32 v98, v4, v66
	ds_read_b128 v[4:7], v98 offset:36864
	ds_read_b128 v[66:69], v97 offset:32
	ds_read_b128 v[70:73], v98 offset:36896
	ds_read_b128 v[8:11], v98 offset:41472
	ds_read_b128 v[74:77], v98 offset:41504
	s_waitcnt lgkmcnt(4)
	v_mfma_f32_32x32x16_bf16 v[48:63], v[0:3], v[4:7], 0
	s_waitcnt lgkmcnt(1)
	v_mfma_f32_32x32x16_bf16 v[32:47], v[0:3], v[8:11], 0
	ds_read_b128 v[0:3], v97 offset:4608
	ds_read_b128 v[84:87], v97 offset:4640
	s_waitcnt lgkmcnt(1)
	v_mfma_f32_32x32x16_bf16 v[16:31], v[0:3], v[4:7], 0
	v_mfma_f32_32x32x16_bf16 v[0:15], v[0:3], v[8:11], 0
	v_mfma_f32_32x32x16_bf16 v[48:63], v[66:69], v[70:73], v[48:63]
	v_mfma_f32_32x32x16_bf16 v[32:47], v[66:69], v[74:77], v[32:47]
	s_waitcnt lgkmcnt(0)
	v_mfma_f32_32x32x16_bf16 v[16:31], v[84:87], v[70:73], v[16:31]
	v_mfma_f32_32x32x16_bf16 v[0:15], v[84:87], v[74:77], v[0:15]
	ds_read_b128 v[66:69], v97 offset:64
	ds_read_b128 v[70:73], v98 offset:36928
	ds_read_b128 v[74:77], v97 offset:96
	ds_read_b128 v[84:87], v98 offset:36960
	ds_read_b128 v[88:91], v98 offset:41536
	ds_read_b128 v[104:107], v98 offset:41568
	s_waitcnt lgkmcnt(4)
	v_mfma_f32_32x32x16_bf16 v[48:63], v[66:69], v[70:73], v[48:63]
	s_waitcnt lgkmcnt(1)
	v_mfma_f32_32x32x16_bf16 v[32:47], v[66:69], v[88:91], v[32:47]
	ds_read_b128 v[66:69], v97 offset:4672
	ds_read_b128 v[108:111], v97 offset:4704
	s_waitcnt lgkmcnt(1)
	v_mfma_f32_32x32x16_bf16 v[16:31], v[66:69], v[70:73], v[16:31]
	v_mfma_f32_32x32x16_bf16 v[0:15], v[66:69], v[88:91], v[0:15]
	s_waitcnt vmcnt(1)
	v_mul_f32_e32 v66, 0x3fb8aa3b, v78
	s_waitcnt vmcnt(0)
	v_mul_f32_e32 v67, 0x3fb8aa3b, v79
	v_exp_f32_e32 v67, v67
	v_exp_f32_e32 v66, v66
	v_mul_f32_e32 v101, 0xbfb8aa3b, v67
	v_mfma_f32_32x32x16_bf16 v[48:63], v[74:77], v[84:87], v[48:63]
	v_mov_b32_e32 v67, s80
	v_mul_f32_e32 v66, 0xbfb8aa3b, v66
	v_cndmask_b32_e32 v67, v67, v83, vcc
	v_mfma_f32_32x32x16_bf16 v[32:47], v[74:77], v[104:107], v[32:47]
	s_waitcnt lgkmcnt(0)
	v_mfma_f32_32x32x16_bf16 v[16:31], v[108:111], v[84:87], v[16:31]
	ds_read_b128 v[68:71], v97 offset:18432
	ds_read_b128 v[72:75], v97 offset:18464
	ds_read_b128 v[76:79], v97 offset:23040
	ds_read_b128 v[84:87], v97 offset:23072
	v_mfma_f32_32x32x16_bf16 v[0:15], v[108:111], v[104:107], v[0:15]
	ds_read_b128 v[88:91], v98 offset:55296
	ds_read_b128 v[104:107], v98 offset:55328
	ds_read_b128 v[108:111], v98 offset:59904
	ds_read_b128 v[112:115], v98 offset:59936
	ds_read_b128 v[116:119], v97 offset:18496
	ds_read_b128 v[120:123], v97 offset:18528
	ds_read_b128 v[124:127], v97 offset:23104
	ds_read_b128 v[142:145], v97 offset:23136
	ds_read_b128 v[146:149], v98 offset:55360
	ds_read_b128 v[150:153], v98 offset:55392
	ds_read_b128 v[154:157], v98 offset:59968
	ds_read_b128 v[158:161], v98 offset:60000
	s_waitcnt lgkmcnt(0)
	s_barrier
	v_mfma_f32_32x32x16_bf16 v[48:63], v[68:71], v[88:91], v[48:63]
	v_mfma_f32_32x32x16_bf16 v[48:63], v[72:75], v[104:107], v[48:63]
	v_mfma_f32_32x32x16_bf16 v[32:47], v[68:71], v[108:111], v[32:47]
	v_sub_u32_e32 v68, v95, v94
	v_mul_u32_u24_e32 v70, 0x90, v95
	v_sub_u32_e32 v69, 0, v68
	v_max_i32_e32 v69, v68, v69
	v_cvt_f32_u32_e32 v69, v69
	v_cmp_lt_i32_e32 vcc, 0, v68
	v_mfma_f32_32x32x16_bf16 v[48:63], v[116:119], v[146:149], v[48:63]
	v_cmp_gt_i32_e64 s[0:1], 0, v68
	v_cndmask_b32_e32 v71, v101, v66, vcc
	v_mul_f32_e32 v69, v71, v69
	v_exp_f32_e32 v69, v69
	v_lshlrev_b32_e32 v71, 1, v92
	v_cmp_ne_u32_e32 vcc, 0, v68
	v_add3_u32 v67, v67, v70, v71
	v_mfma_f32_32x32x16_bf16 v[48:63], v[120:123], v[150:153], v[48:63]
	v_cndmask_b32_e32 v69, 2.0, v69, vcc
	v_add_co_u32_e32 v70, vcc, 1, v68
	v_sub_u32_e32 v71, 0, v70
	v_max_i32_e32 v71, v70, v71
	v_cvt_f32_u32_e32 v71, v71
	s_nop 6
	v_mul_f32_e32 v83, 0x3db504f3, v48
	v_cndmask_b32_e64 v48, v66, v101, s[0:1]
	v_mul_f32_e32 v48, v48, v71
	v_mul_f32_e32 v71, v83, v69
	v_add_u32_e32 v83, 2, v68
	v_mfma_f32_32x32x16_bf16 v[16:31], v[76:79], v[88:91], v[16:31]
	v_exp_f32_e32 v48, v48
	v_cvt_pk_bf16_f32 v71, v71, s0
	ds_write_b16 v67, v71
	v_mul_f32_e32 v49, 0x3db504f3, v49
	v_cndmask_b32_e64 v71, v48, 2.0, vcc
	v_cmp_lt_i32_e32 vcc, -2, v68
	v_mul_f32_e32 v71, v49, v71
	v_mfma_f32_32x32x16_bf16 v[0:15], v[76:79], v[108:111], v[0:15]
	v_sub_u32_e32 v76, 0, v83
	v_max_i32_e32 v76, v83, v76
	v_cvt_f32_u32_e32 v76, v76
	v_cndmask_b32_e32 v49, v101, v66, vcc
	v_cvt_pk_bf16_f32 v71, v71, s0
	v_cmp_ne_u32_e32 vcc, 0, v83
	v_mul_f32_e32 v49, v49, v76
	v_mfma_f32_32x32x16_bf16 v[32:47], v[72:75], v[112:115], v[32:47]
	v_add_u32_e32 v72, 3, v68
	v_exp_f32_e32 v49, v49
	v_sub_u32_e32 v73, 0, v72
	v_max_i32_e32 v73, v72, v73
	v_cvt_f32_u32_e32 v73, v73
	ds_write_b16 v67, v71 offset:144
	v_cndmask_b32_e32 v71, 2.0, v49, vcc
	v_mul_f32_e32 v50, 0x3db504f3, v50
	v_cmp_lt_i32_e32 vcc, -3, v68
	v_mul_f32_e32 v71, v50, v71
	v_cvt_pk_bf16_f32 v71, v71, s0
	v_cndmask_b32_e32 v50, v101, v66, vcc
	v_mul_f32_e32 v50, v50, v73
	v_add_u32_e32 v73, 8, v68
	v_exp_f32_e32 v50, v50
	v_sub_u32_e32 v74, 0, v73
	v_max_i32_e32 v74, v73, v74
	v_cvt_f32_u32_e32 v74, v74
	v_cmp_ne_u32_e32 vcc, 0, v72
	ds_write_b16 v67, v71 offset:288
	v_mul_f32_e32 v51, 0x3db504f3, v51
	v_cndmask_b32_e32 v71, 2.0, v50, vcc
	v_cmp_lt_i32_e32 vcc, -8, v68
	v_mul_f32_e32 v71, v51, v71
	v_cvt_pk_bf16_f32 v71, v71, s0
	v_cndmask_b32_e32 v51, v101, v66, vcc
	v_mul_f32_e32 v51, v51, v74
	v_add_u32_e32 v74, 9, v68
	v_exp_f32_e32 v51, v51
	v_sub_u32_e32 v75, 0, v74
	v_max_i32_e32 v75, v74, v75
	v_cvt_f32_u32_e32 v75, v75
	v_cmp_ne_u32_e32 vcc, 0, v73
	ds_write_b16 v67, v71 offset:432
	v_mul_f32_e32 v52, 0x3db504f3, v52
	v_cndmask_b32_e32 v71, 2.0, v51, vcc
	v_cmp_lt_i32_e32 vcc, -9, v68
	v_mul_f32_e32 v71, v52, v71
	v_cvt_pk_bf16_f32 v71, v71, s0
	v_cndmask_b32_e32 v52, v101, v66, vcc
	v_mul_f32_e32 v52, v52, v75
	v_add_u32_e32 v75, 10, v68
	v_exp_f32_e32 v52, v52
	v_sub_u32_e32 v76, 0, v75
	v_max_i32_e32 v76, v75, v76
	v_cvt_f32_u32_e32 v76, v76
	v_cmp_ne_u32_e32 vcc, 0, v74
	ds_write_b16 v67, v71 offset:1152
	v_mul_f32_e32 v53, 0x3db504f3, v53
	v_cndmask_b32_e32 v71, 2.0, v52, vcc
	v_cmp_lt_i32_e32 vcc, -10, v68
	v_mul_f32_e32 v71, v53, v71
	v_cvt_pk_bf16_f32 v71, v71, s0
	v_cndmask_b32_e32 v53, v101, v66, vcc
	v_mul_f32_e32 v53, v53, v76
	v_add_u32_e32 v76, 11, v68
	v_exp_f32_e32 v53, v53
	v_sub_u32_e32 v77, 0, v76
	v_max_i32_e32 v77, v76, v77
	v_cvt_f32_u32_e32 v77, v77
	v_cmp_ne_u32_e32 vcc, 0, v75
	ds_write_b16 v67, v71 offset:1296
	v_mul_f32_e32 v54, 0x3db504f3, v54
	v_cndmask_b32_e32 v71, 2.0, v53, vcc
	v_cmp_lt_i32_e32 vcc, -11, v68
	v_mul_f32_e32 v71, v54, v71
	v_cvt_pk_bf16_f32 v71, v71, s0
	v_cndmask_b32_e32 v54, v101, v66, vcc
	v_mul_f32_e32 v54, v54, v77
	v_add_u32_e32 v77, 16, v68
	v_exp_f32_e32 v54, v54
	v_sub_u32_e32 v78, 0, v77
	v_max_i32_e32 v78, v77, v78
	v_cvt_f32_u32_e32 v78, v78
	v_cmp_ne_u32_e32 vcc, 0, v76
	ds_write_b16 v67, v71 offset:1440
	v_mul_f32_e32 v55, 0x3db504f3, v55
	v_cndmask_b32_e32 v71, 2.0, v54, vcc
	v_cmp_lt_i32_e32 vcc, -16, v68
	v_mul_f32_e32 v71, v55, v71
	v_cvt_pk_bf16_f32 v71, v71, s0
	v_cndmask_b32_e32 v55, v101, v66, vcc
	v_mul_f32_e32 v55, v55, v78
	v_add_u32_e32 v78, 17, v68
	v_exp_f32_e32 v55, v55
	v_sub_u32_e32 v79, 0, v78
	v_max_i32_e32 v79, v78, v79
	v_cvt_f32_u32_e32 v79, v79
	v_cmp_ne_u32_e32 vcc, 0, v77
	s_movk_i32 s0, 0xffef
	ds_write_b16 v67, v71 offset:1584
	v_cndmask_b32_e32 v71, 2.0, v55, vcc
	v_mul_f32_e32 v56, 0x3db504f3, v56
	v_cmp_lt_i32_e32 vcc, s0, v68
	v_mul_f32_e32 v71, v56, v71
	v_mfma_f32_32x32x16_bf16 v[16:31], v[84:87], v[104:107], v[16:31]
	v_cndmask_b32_e32 v56, v101, v66, vcc
	v_mul_f32_e32 v56, v56, v79
	v_add_u32_e32 v79, 18, v68
	v_exp_f32_e32 v56, v56
	v_cvt_pk_bf16_f32 v71, v71, s0
	v_cmp_ne_u32_e32 vcc, 0, v78
	s_movk_i32 s0, 0xffee
	v_mfma_f32_32x32x16_bf16 v[0:15], v[84:87], v[112:115], v[0:15]
	v_sub_u32_e32 v84, 0, v79
	v_max_i32_e32 v84, v79, v84
	v_cvt_f32_u32_e32 v84, v84
	ds_write_b16 v67, v71 offset:2304
	v_cndmask_b32_e32 v71, 2.0, v56, vcc
	v_mul_f32_e32 v57, 0x3db504f3, v57
	v_cmp_lt_i32_e32 vcc, s0, v68
	v_mul_f32_e32 v71, v57, v71
	v_cvt_pk_bf16_f32 v71, v71, s0
	v_cndmask_b32_e32 v57, v101, v66, vcc
	v_mul_f32_e32 v57, v57, v84
	v_add_u32_e32 v84, 19, v68
	v_exp_f32_e32 v57, v57
	v_sub_u32_e32 v85, 0, v84
	v_max_i32_e32 v85, v84, v85
	v_cvt_f32_u32_e32 v85, v85
	v_cmp_ne_u32_e32 vcc, 0, v79
	s_movk_i32 s0, 0xffed
	ds_write_b16 v67, v71 offset:2448
	v_cndmask_b32_e32 v71, 2.0, v57, vcc
	v_mul_f32_e32 v58, 0x3db504f3, v58
	v_cmp_lt_i32_e32 vcc, s0, v68
	v_mul_f32_e32 v71, v58, v71
	v_cvt_pk_bf16_f32 v71, v71, s0
	v_cndmask_b32_e32 v58, v101, v66, vcc
	v_mul_f32_e32 v58, v58, v85
	v_add_u32_e32 v85, 24, v68
	v_exp_f32_e32 v58, v58
	v_sub_u32_e32 v86, 0, v85
	v_max_i32_e32 v86, v85, v86
	v_cvt_f32_u32_e32 v86, v86
	v_cmp_ne_u32_e32 vcc, 0, v84
	s_movk_i32 s0, 0xffe8
	ds_write_b16 v67, v71 offset:2592
	v_cndmask_b32_e32 v71, 2.0, v58, vcc
	v_mul_f32_e32 v59, 0x3db504f3, v59
	v_cmp_lt_i32_e32 vcc, s0, v68
	v_mul_f32_e32 v71, v59, v71
	v_cvt_pk_bf16_f32 v71, v71, s0
	v_cndmask_b32_e32 v59, v101, v66, vcc
	v_mul_f32_e32 v59, v59, v86
	v_add_u32_e32 v86, 25, v68
	v_exp_f32_e32 v59, v59
	v_sub_u32_e32 v87, 0, v86
	v_max_i32_e32 v87, v86, v87
	v_cvt_f32_u32_e32 v87, v87
	v_cmp_ne_u32_e32 vcc, 0, v85
	s_movk_i32 s0, 0xffe7
	ds_write_b16 v67, v71 offset:2736
	v_cndmask_b32_e32 v71, 2.0, v59, vcc
	v_mul_f32_e32 v60, 0x3db504f3, v60
	v_cmp_lt_i32_e32 vcc, s0, v68
	v_mul_f32_e32 v71, v60, v71
	v_cvt_pk_bf16_f32 v71, v71, s0
	v_cndmask_b32_e32 v60, v101, v66, vcc
	v_mul_f32_e32 v60, v60, v87
	v_add_u32_e32 v87, 26, v68
	v_exp_f32_e32 v60, v60
	v_sub_u32_e32 v88, 0, v87
	v_max_i32_e32 v88, v87, v88
	v_cvt_f32_u32_e32 v88, v88
	v_cmp_ne_u32_e32 vcc, 0, v86
	s_movk_i32 s0, 0xffe6
	ds_write_b16 v67, v71 offset:3456
	v_cndmask_b32_e32 v71, 2.0, v60, vcc
	v_mul_f32_e32 v61, 0x3db504f3, v61
	v_cmp_lt_i32_e32 vcc, s0, v68
	v_mul_f32_e32 v71, v61, v71
	v_cvt_pk_bf16_f32 v71, v71, s0
	v_cndmask_b32_e32 v61, v101, v66, vcc
	v_mul_f32_e32 v61, v61, v88
	v_add_u32_e32 v88, 27, v68
	v_exp_f32_e32 v61, v61
	v_sub_u32_e32 v89, 0, v88
	v_max_i32_e32 v89, v88, v89
	v_cvt_f32_u32_e32 v89, v89
	v_cmp_ne_u32_e32 vcc, 0, v87
	s_movk_i32 s0, 0xffe5
	ds_write_b16 v67, v71 offset:3600
	v_cndmask_b32_e32 v71, 2.0, v61, vcc
	v_mul_f32_e32 v62, 0x3db504f3, v62
	v_cmp_lt_i32_e32 vcc, s0, v68
	v_mul_f32_e32 v71, v62, v71
	v_mfma_f32_32x32x16_bf16 v[32:47], v[116:119], v[154:157], v[32:47]
	v_cndmask_b32_e32 v62, v101, v66, vcc
	v_mul_f32_e32 v62, v62, v89
	v_exp_f32_e32 v62, v62
	v_subrev_u32_e32 v89, 32, v68
	v_sub_u32_e32 v90, 32, v68
	v_max_i32_e32 v89, v89, v90
	v_cvt_f32_u32_e32 v89, v89
	v_cvt_pk_bf16_f32 v71, v71, s0
	v_cmp_ne_u32_e32 vcc, 0, v88
	ds_write_b16 v67, v71 offset:3744
	v_mul_f32_e32 v63, 0x3db504f3, v63
	v_cndmask_b32_e32 v71, 2.0, v62, vcc
	v_cmp_lt_i32_e32 vcc, 32, v68
	v_mul_f32_e32 v63, v63, v71
	v_mfma_f32_32x32x16_bf16 v[32:47], v[120:123], v[158:161], v[32:47]
	v_cndmask_b32_e32 v71, v101, v66, vcc
	v_mul_f32_e32 v71, v71, v89
	v_exp_f32_e32 v71, v71
	v_cvt_pk_bf16_f32 v63, v63, s0
	v_cmp_ne_u32_e32 vcc, 32, v68
	ds_write_b16 v67, v63 offset:3888
	v_sub_u32_e32 v89, 31, v68
	v_cndmask_b32_e32 v63, 2.0, v71, vcc
	v_subrev_u32_e32 v71, 31, v68
	v_max_i32_e32 v71, v71, v89
	v_cvt_f32_u32_e32 v71, v71
	s_nop 0
	v_mul_f32_e32 v32, 0x3db504f3, v32
	v_cmp_lt_i32_e32 vcc, 31, v68
	v_mul_f32_e32 v32, v32, v63
	v_cvt_pk_bf16_f32 v32, v32, s0
	v_cndmask_b32_e32 v63, v101, v66, vcc
	v_mul_f32_e32 v63, v63, v71
	v_exp_f32_e32 v63, v63
	v_cmp_ne_u32_e32 vcc, 32, v70
	ds_write_b16 v67, v32 offset:64
	v_sub_u32_e32 v70, 30, v68
	v_cndmask_b32_e32 v32, 2.0, v63, vcc
	v_subrev_u32_e32 v63, 30, v68
	v_max_i32_e32 v63, v63, v70
	v_cvt_f32_u32_e32 v63, v63
	v_mul_f32_e32 v33, 0x3db504f3, v33
	v_cmp_lt_i32_e32 vcc, 30, v68
	v_mul_f32_e32 v32, v33, v32
	v_cvt_pk_bf16_f32 v32, v32, s0
	v_cndmask_b32_e32 v33, v101, v66, vcc
	v_mul_f32_e32 v33, v33, v63
	v_exp_f32_e32 v33, v33
	v_cmp_ne_u32_e32 vcc, 32, v83
	ds_write_b16 v67, v32 offset:208
	v_sub_u32_e32 v63, 29, v68
	v_cndmask_b32_e32 v32, 2.0, v33, vcc
	v_mul_f32_e32 v33, 0x3db504f3, v34
	v_subrev_u32_e32 v34, 29, v68
	v_max_i32_e32 v34, v34, v63
	v_cvt_f32_u32_e32 v34, v34
	v_cmp_lt_i32_e32 vcc, 29, v68
	v_mul_f32_e32 v32, v33, v32
	v_cvt_pk_bf16_f32 v32, v32, s0
	v_cndmask_b32_e32 v33, v101, v66, vcc
	v_mul_f32_e32 v33, v33, v34
	v_exp_f32_e32 v33, v33
	v_cmp_ne_u32_e32 vcc, 32, v72
	ds_write_b16 v67, v32 offset:352
	v_subrev_u32_e32 v34, 24, v68
	v_cndmask_b32_e32 v32, 2.0, v33, vcc
	v_mul_f32_e32 v33, 0x3db504f3, v35
	v_sub_u32_e32 v35, 24, v68
	v_max_i32_e32 v34, v34, v35
	v_cvt_f32_u32_e32 v34, v34
	v_cmp_lt_i32_e32 vcc, 24, v68
	v_mul_f32_e32 v32, v33, v32
	v_sub_u32_e32 v35, 23, v68
	v_cndmask_b32_e32 v33, v101, v66, vcc
	v_mul_f32_e32 v33, v33, v34
	v_exp_f32_e32 v33, v33
	v_subrev_u32_e32 v34, 23, v68
	v_max_i32_e32 v34, v34, v35
	v_cvt_f32_u32_e32 v34, v34
	v_cvt_pk_bf16_f32 v32, v32, s0
	v_cmp_ne_u32_e32 vcc, 32, v73
	ds_write_b16 v67, v32 offset:496
	v_sub_u32_e32 v35, 22, v68
	v_cndmask_b32_e32 v32, 2.0, v33, vcc
	v_mul_f32_e32 v33, 0x3db504f3, v36
	v_cmp_lt_i32_e32 vcc, 23, v68
	v_mul_f32_e32 v32, v33, v32
	v_cvt_pk_bf16_f32 v32, v32, s0
	v_cndmask_b32_e32 v33, v101, v66, vcc
	v_mul_f32_e32 v33, v33, v34
	v_exp_f32_e32 v33, v33
	v_subrev_u32_e32 v34, 22, v68
	v_max_i32_e32 v34, v34, v35
	v_cvt_f32_u32_e32 v34, v34
	v_cmp_ne_u32_e32 vcc, 32, v74
	ds_write_b16 v67, v32 offset:1216
	v_sub_u32_e32 v35, 21, v68
	v_cndmask_b32_e32 v32, 2.0, v33, vcc
	v_mul_f32_e32 v33, 0x3db504f3, v37
	v_cmp_lt_i32_e32 vcc, 22, v68
	v_mul_f32_e32 v32, v33, v32
	v_cvt_pk_bf16_f32 v32, v32, s0
	v_cndmask_b32_e32 v33, v101, v66, vcc
	v_mul_f32_e32 v33, v33, v34
	v_exp_f32_e32 v33, v33
	v_subrev_u32_e32 v34, 21, v68
	v_max_i32_e32 v34, v34, v35
	v_cvt_f32_u32_e32 v34, v34
	v_cmp_ne_u32_e32 vcc, 32, v75
	ds_write_b16 v67, v32 offset:1360
	v_sub_u32_e32 v35, 16, v68
	v_cndmask_b32_e32 v32, 2.0, v33, vcc
	v_mul_f32_e32 v33, 0x3db504f3, v38
	v_cmp_lt_i32_e32 vcc, 21, v68
	v_mul_f32_e32 v32, v33, v32
	v_cvt_pk_bf16_f32 v32, v32, s0
	v_cndmask_b32_e32 v33, v101, v66, vcc
	v_mul_f32_e32 v33, v33, v34
	v_exp_f32_e32 v33, v33
	v_add_u32_e32 v34, -16, v68
	v_max_i32_e32 v34, v34, v35
	v_cvt_f32_u32_e32 v34, v34
	v_cmp_ne_u32_e32 vcc, 32, v76
	ds_write_b16 v67, v32 offset:1504
	v_sub_u32_e32 v35, 15, v68
	v_cndmask_b32_e32 v32, 2.0, v33, vcc
	v_mul_f32_e32 v33, 0x3db504f3, v39
	v_cmp_lt_i32_e32 vcc, 16, v68
	v_mul_f32_e32 v32, v33, v32
	v_cvt_pk_bf16_f32 v32, v32, s0
	v_cndmask_b32_e32 v33, v101, v66, vcc
	v_mul_f32_e32 v33, v33, v34
	v_exp_f32_e32 v33, v33
	v_add_u32_e32 v34, -15, v68
	v_max_i32_e32 v34, v34, v35
	v_cvt_f32_u32_e32 v34, v34
	v_cmp_ne_u32_e32 vcc, 32, v77
	ds_write_b16 v67, v32 offset:1648
	v_sub_u32_e32 v35, 14, v68
	v_cndmask_b32_e32 v32, 2.0, v33, vcc
	v_mul_f32_e32 v33, 0x3db504f3, v40
	v_cmp_lt_i32_e32 vcc, 15, v68
	v_mul_f32_e32 v32, v33, v32
	v_cvt_pk_bf16_f32 v32, v32, s0
	v_cndmask_b32_e32 v33, v101, v66, vcc
	v_mul_f32_e32 v33, v33, v34
	v_exp_f32_e32 v33, v33
	v_add_u32_e32 v34, -14, v68
	v_max_i32_e32 v34, v34, v35
	v_cvt_f32_u32_e32 v34, v34
	v_cmp_ne_u32_e32 vcc, 32, v78
	ds_write_b16 v67, v32 offset:2368
	v_sub_u32_e32 v35, 13, v68
	v_cndmask_b32_e32 v32, 2.0, v33, vcc
	v_mul_f32_e32 v33, 0x3db504f3, v41
	v_cmp_lt_i32_e32 vcc, 14, v68
	v_mul_f32_e32 v32, v33, v32
	v_cvt_pk_bf16_f32 v32, v32, s0
	v_cndmask_b32_e32 v33, v101, v66, vcc
	v_mul_f32_e32 v33, v33, v34
	v_exp_f32_e32 v33, v33
	v_add_u32_e32 v34, -13, v68
	v_max_i32_e32 v34, v34, v35
	v_cvt_f32_u32_e32 v34, v34
	v_cmp_ne_u32_e32 vcc, 32, v79
	ds_write_b16 v67, v32 offset:2512
	v_sub_u32_e32 v35, 8, v68
	v_cndmask_b32_e32 v32, 2.0, v33, vcc
	v_mul_f32_e32 v33, 0x3db504f3, v42
	v_cmp_lt_i32_e32 vcc, 13, v68
	v_mul_f32_e32 v32, v33, v32
	v_cvt_pk_bf16_f32 v32, v32, s0
	v_cndmask_b32_e32 v33, v101, v66, vcc
	v_mul_f32_e32 v33, v33, v34
	v_exp_f32_e32 v33, v33
	v_add_u32_e32 v34, -8, v68
	v_max_i32_e32 v34, v34, v35
	v_cvt_f32_u32_e32 v34, v34
	v_cmp_ne_u32_e32 vcc, 32, v84
	ds_write_b16 v67, v32 offset:2656
	v_sub_u32_e32 v35, 7, v68
	v_cndmask_b32_e32 v32, 2.0, v33, vcc
	v_mul_f32_e32 v33, 0x3db504f3, v43
	v_cmp_lt_i32_e32 vcc, 8, v68
	v_mul_f32_e32 v32, v33, v32
	v_cvt_pk_bf16_f32 v32, v32, s0
	v_cndmask_b32_e32 v33, v101, v66, vcc
	v_mul_f32_e32 v33, v33, v34
	v_exp_f32_e32 v33, v33
	v_add_u32_e32 v34, -7, v68
	v_max_i32_e32 v34, v34, v35
	v_cvt_f32_u32_e32 v34, v34
	v_cmp_ne_u32_e32 vcc, 32, v85
	ds_write_b16 v67, v32 offset:2800
	v_sub_u32_e32 v35, 6, v68
	v_cndmask_b32_e32 v32, 2.0, v33, vcc
	v_mul_f32_e32 v33, 0x3db504f3, v44
	v_cmp_lt_i32_e32 vcc, 7, v68
	v_mul_f32_e32 v32, v33, v32
	v_cvt_pk_bf16_f32 v32, v32, s0
	v_cndmask_b32_e32 v33, v101, v66, vcc
	v_mul_f32_e32 v33, v33, v34
	v_exp_f32_e32 v33, v33
	v_add_u32_e32 v34, -6, v68
	v_max_i32_e32 v34, v34, v35
	v_cvt_f32_u32_e32 v34, v34
	v_cmp_ne_u32_e32 vcc, 32, v86
	ds_write_b16 v67, v32 offset:3520
	v_sub_u32_e32 v35, 5, v68
	v_cndmask_b32_e32 v32, 2.0, v33, vcc
	v_mul_f32_e32 v33, 0x3db504f3, v45
	v_cmp_lt_i32_e32 vcc, 6, v68
	v_mul_f32_e32 v32, v33, v32
	v_cvt_pk_bf16_f32 v32, v32, s0
	v_cndmask_b32_e32 v33, v101, v66, vcc
	v_mul_f32_e32 v33, v33, v34
	v_exp_f32_e32 v33, v33
	v_add_u32_e32 v34, -5, v68
	v_max_i32_e32 v34, v34, v35
	v_cvt_f32_u32_e32 v34, v34
	v_cmp_ne_u32_e32 vcc, 32, v87
	ds_write_b16 v67, v32 offset:3664
	v_mfma_f32_32x32x16_bf16 v[16:31], v[124:127], v[146:149], v[16:31]
	v_cndmask_b32_e32 v32, 2.0, v33, vcc
	v_mul_f32_e32 v33, 0x3db504f3, v46
	v_cmp_lt_i32_e32 vcc, 5, v68
	v_mul_f32_e32 v32, v33, v32
	v_cvt_pk_bf16_f32 v32, v32, s0
	v_cndmask_b32_e32 v33, v101, v66, vcc
	v_mul_f32_e32 v33, v33, v34
	v_exp_f32_e32 v33, v33
	v_cmp_ne_u32_e32 vcc, 32, v88
	ds_write_b16 v67, v32 offset:3808
	v_mfma_f32_32x32x16_bf16 v[16:31], v[142:145], v[150:153], v[16:31]
	v_cndmask_b32_e32 v32, 2.0, v33, vcc
	v_mul_f32_e32 v33, 0x3db504f3, v47
	v_mul_f32_e32 v32, v33, v32
	v_add_u32_e32 v33, 32, v68
	v_sub_u32_e32 v34, 0, v33
	v_max_i32_e32 v34, v33, v34
	v_cvt_f32_u32_e32 v34, v34
	v_cvt_pk_bf16_f32 v32, v32, s0
	s_movk_i32 s0, 0xffe0
	v_cmp_lt_i32_e32 vcc, s0, v68
	ds_write_b16 v67, v32 offset:3952
	s_movk_i32 s0, 0xffdf
	v_cndmask_b32_e32 v35, v101, v66, vcc
	v_mul_f32_e32 v34, v35, v34
	v_exp_f32_e32 v34, v34
	v_cmp_ne_u32_e32 vcc, 0, v33
	v_add_u32_e32 v33, 33, v68
	v_mul_f32_e32 v16, 0x3db504f3, v16
	v_cndmask_b32_e32 v32, 2.0, v34, vcc
	v_sub_u32_e32 v34, 0, v33
	v_max_i32_e32 v34, v33, v34
	v_cvt_f32_u32_e32 v34, v34
	v_cmp_lt_i32_e32 vcc, s0, v68
	v_mul_f32_e32 v16, v16, v32
	v_cvt_pk_bf16_f32 v16, v16, s0
	v_cndmask_b32_e32 v32, v101, v66, vcc
	v_mul_f32_e32 v32, v32, v34
	v_exp_f32_e32 v32, v32
	v_cmp_ne_u32_e32 vcc, 0, v33
	ds_write_b16 v67, v16 offset:4608
	s_movk_i32 s0, 0xffde
	v_cndmask_b32_e32 v16, 2.0, v32, vcc
	v_add_u32_e32 v32, 34, v68
	v_sub_u32_e32 v34, 0, v32
	v_max_i32_e32 v34, v32, v34
	v_cvt_f32_u32_e32 v34, v34
	v_mul_f32_e32 v17, 0x3db504f3, v17
	v_cmp_lt_i32_e32 vcc, s0, v68
	v_mul_f32_e32 v16, v17, v16
	v_cvt_pk_bf16_f32 v16, v16, s0
	v_cndmask_b32_e32 v17, v101, v66, vcc
	v_mul_f32_e32 v17, v17, v34
	v_exp_f32_e32 v17, v17
	v_cmp_ne_u32_e32 vcc, 0, v32
	ds_write_b16 v67, v16 offset:4752
	s_movk_i32 s0, 0xffdd
	v_cndmask_b32_e32 v16, 2.0, v17, vcc
	v_mul_f32_e32 v17, 0x3db504f3, v18
	v_add_u32_e32 v18, 35, v68
	v_sub_u32_e32 v34, 0, v18
	v_max_i32_e32 v34, v18, v34
	v_cvt_f32_u32_e32 v34, v34
	v_cmp_lt_i32_e32 vcc, s0, v68
	v_mul_f32_e32 v16, v17, v16
	v_cvt_pk_bf16_f32 v16, v16, s0
	v_cndmask_b32_e32 v17, v101, v66, vcc
	v_mul_f32_e32 v17, v17, v34
	v_exp_f32_e32 v17, v17
	v_cmp_ne_u32_e32 vcc, 0, v18
	ds_write_b16 v67, v16 offset:4896
	s_movk_i32 s0, 0xffd8
	v_cndmask_b32_e32 v16, 2.0, v17, vcc
	v_mul_f32_e32 v17, 0x3db504f3, v19
	v_add_u32_e32 v19, 40, v68
	v_sub_u32_e32 v34, 0, v19
	v_max_i32_e32 v34, v19, v34
	v_cvt_f32_u32_e32 v34, v34
	v_cmp_lt_i32_e32 vcc, s0, v68
	v_mul_f32_e32 v16, v17, v16
	v_cvt_pk_bf16_f32 v16, v16, s0
	v_cndmask_b32_e32 v17, v101, v66, vcc
	v_mul_f32_e32 v17, v17, v34
	v_exp_f32_e32 v17, v17
	v_cmp_ne_u32_e32 vcc, 0, v19
	ds_write_b16 v67, v16 offset:5040
	s_movk_i32 s0, 0xffd7
	v_cndmask_b32_e32 v16, 2.0, v17, vcc
	v_mul_f32_e32 v17, 0x3db504f3, v20
	v_add_u32_e32 v20, 41, v68
	v_sub_u32_e32 v34, 0, v20
	v_max_i32_e32 v34, v20, v34
	v_cvt_f32_u32_e32 v34, v34
	v_cmp_lt_i32_e32 vcc, s0, v68
	v_mul_f32_e32 v16, v17, v16
	v_cvt_pk_bf16_f32 v16, v16, s0
	v_cndmask_b32_e32 v17, v101, v66, vcc
	v_mul_f32_e32 v17, v17, v34
	v_exp_f32_e32 v17, v17
	v_cmp_ne_u32_e32 vcc, 0, v20
	ds_write_b16 v67, v16 offset:5760
	s_movk_i32 s0, 0xffd6
	v_cndmask_b32_e32 v16, 2.0, v17, vcc
	v_mul_f32_e32 v17, 0x3db504f3, v21
	v_add_u32_e32 v21, 42, v68
	v_sub_u32_e32 v34, 0, v21
	v_max_i32_e32 v34, v21, v34
	v_cvt_f32_u32_e32 v34, v34
	v_cmp_lt_i32_e32 vcc, s0, v68
	v_mul_f32_e32 v16, v17, v16
	v_cvt_pk_bf16_f32 v16, v16, s0
	v_cndmask_b32_e32 v17, v101, v66, vcc
	v_mul_f32_e32 v17, v17, v34
	v_exp_f32_e32 v17, v17
	v_cmp_ne_u32_e32 vcc, 0, v21
	ds_write_b16 v67, v16 offset:5904
	s_movk_i32 s0, 0xffd5
	v_cndmask_b32_e32 v16, 2.0, v17, vcc
	v_mul_f32_e32 v17, 0x3db504f3, v22
	v_add_u32_e32 v22, 43, v68
	v_sub_u32_e32 v34, 0, v22
	v_max_i32_e32 v34, v22, v34
	v_cvt_f32_u32_e32 v34, v34
	v_cmp_lt_i32_e32 vcc, s0, v68
	v_mul_f32_e32 v16, v17, v16
	v_cvt_pk_bf16_f32 v16, v16, s0
	v_cndmask_b32_e32 v17, v101, v66, vcc
	v_mul_f32_e32 v17, v17, v34
	v_exp_f32_e32 v17, v17
	v_cmp_ne_u32_e32 vcc, 0, v22
	ds_write_b16 v67, v16 offset:6048
	s_movk_i32 s0, 0xffd0
	v_cndmask_b32_e32 v16, 2.0, v17, vcc
	v_mul_f32_e32 v17, 0x3db504f3, v23
	v_add_u32_e32 v23, 48, v68
	v_sub_u32_e32 v34, 0, v23
	v_max_i32_e32 v34, v23, v34
	v_cvt_f32_u32_e32 v34, v34
	v_cmp_lt_i32_e32 vcc, s0, v68
	v_mul_f32_e32 v16, v17, v16
	v_cvt_pk_bf16_f32 v16, v16, s0
	v_cndmask_b32_e32 v17, v101, v66, vcc
	v_mul_f32_e32 v17, v17, v34
	v_exp_f32_e32 v17, v17
	v_cmp_ne_u32_e32 vcc, 0, v23
	ds_write_b16 v67, v16 offset:6192
	s_movk_i32 s0, 0xffcf
	v_cndmask_b32_e32 v16, 2.0, v17, vcc
	v_mul_f32_e32 v17, 0x3db504f3, v24
	v_add_u32_e32 v24, 49, v68
	v_sub_u32_e32 v34, 0, v24
	v_max_i32_e32 v34, v24, v34
	v_cvt_f32_u32_e32 v34, v34
	v_cmp_lt_i32_e32 vcc, s0, v68
	v_mul_f32_e32 v16, v17, v16
	v_cvt_pk_bf16_f32 v16, v16, s0
	v_cndmask_b32_e32 v17, v101, v66, vcc
	v_mul_f32_e32 v17, v17, v34
	v_exp_f32_e32 v17, v17
	v_cmp_ne_u32_e32 vcc, 0, v24
	ds_write_b16 v67, v16 offset:6912
	s_movk_i32 s0, 0xffce
	v_cndmask_b32_e32 v16, 2.0, v17, vcc
	v_mul_f32_e32 v17, 0x3db504f3, v25
	v_add_u32_e32 v25, 50, v68
	v_sub_u32_e32 v34, 0, v25
	v_max_i32_e32 v34, v25, v34
	v_cvt_f32_u32_e32 v34, v34
	v_cmp_lt_i32_e32 vcc, s0, v68
	v_mul_f32_e32 v16, v17, v16
	v_cvt_pk_bf16_f32 v16, v16, s0
	v_cndmask_b32_e32 v17, v101, v66, vcc
	v_mul_f32_e32 v17, v17, v34
	v_exp_f32_e32 v17, v17
	v_cmp_ne_u32_e32 vcc, 0, v25
	ds_write_b16 v67, v16 offset:7056
	s_movk_i32 s0, 0xffcd
	v_cndmask_b32_e32 v16, 2.0, v17, vcc
	v_mul_f32_e32 v17, 0x3db504f3, v26
	v_add_u32_e32 v26, 51, v68
	v_sub_u32_e32 v34, 0, v26
	v_max_i32_e32 v34, v26, v34
	v_cvt_f32_u32_e32 v34, v34
	v_cmp_lt_i32_e32 vcc, s0, v68
	v_mul_f32_e32 v16, v17, v16
	v_cvt_pk_bf16_f32 v16, v16, s0
	v_cndmask_b32_e32 v17, v101, v66, vcc
	v_mul_f32_e32 v17, v17, v34
	v_exp_f32_e32 v17, v17
	v_cmp_ne_u32_e32 vcc, 0, v26
	ds_write_b16 v67, v16 offset:7200
	s_movk_i32 s0, 0xffc8
	v_cndmask_b32_e32 v16, 2.0, v17, vcc
	v_mul_f32_e32 v17, 0x3db504f3, v27
	v_add_u32_e32 v27, 56, v68
	v_sub_u32_e32 v34, 0, v27
	v_max_i32_e32 v34, v27, v34
	v_cvt_f32_u32_e32 v34, v34
	v_cmp_lt_i32_e32 vcc, s0, v68
	v_mul_f32_e32 v16, v17, v16
	v_cvt_pk_bf16_f32 v16, v16, s0
	v_cndmask_b32_e32 v17, v101, v66, vcc
	v_mul_f32_e32 v17, v17, v34
	v_exp_f32_e32 v17, v17
	v_cmp_ne_u32_e32 vcc, 0, v27
	ds_write_b16 v67, v16 offset:7344
	s_movk_i32 s0, 0xffc7
	v_cndmask_b32_e32 v16, 2.0, v17, vcc
	v_mul_f32_e32 v17, 0x3db504f3, v28
	v_add_u32_e32 v28, 57, v68
	v_sub_u32_e32 v34, 0, v28
	v_max_i32_e32 v34, v28, v34
	v_cvt_f32_u32_e32 v34, v34
	v_cmp_lt_i32_e32 vcc, s0, v68
	v_mul_f32_e32 v16, v17, v16
	v_cvt_pk_bf16_f32 v16, v16, s0
	v_cndmask_b32_e32 v17, v101, v66, vcc
	v_mul_f32_e32 v17, v17, v34
	v_exp_f32_e32 v17, v17
	v_cmp_ne_u32_e32 vcc, 0, v28
	ds_write_b16 v67, v16 offset:8064
	s_movk_i32 s0, 0xffc6
	v_cndmask_b32_e32 v16, 2.0, v17, vcc
	v_mul_f32_e32 v17, 0x3db504f3, v29
	v_add_u32_e32 v29, 58, v68
	v_sub_u32_e32 v34, 0, v29
	v_max_i32_e32 v34, v29, v34
	v_cvt_f32_u32_e32 v34, v34
	v_cmp_lt_i32_e32 vcc, s0, v68
	v_mfma_f32_32x32x16_bf16 v[0:15], v[124:127], v[154:157], v[0:15]
	v_mul_f32_e32 v16, v17, v16
	v_cndmask_b32_e32 v17, v101, v66, vcc
	v_mul_f32_e32 v17, v17, v34
	v_exp_f32_e32 v17, v17
	v_cvt_pk_bf16_f32 v16, v16, s0
	v_cmp_ne_u32_e32 vcc, 0, v29
	ds_write_b16 v67, v16 offset:8208
	v_mfma_f32_32x32x16_bf16 v[0:15], v[142:145], v[158:161], v[0:15]
	v_cndmask_b32_e32 v16, 2.0, v17, vcc
	v_mul_f32_e32 v17, 0x3db504f3, v30
	v_add_u32_e32 v30, 59, v68
	v_sub_u32_e32 v34, 0, v30
	v_max_i32_e32 v34, v30, v34
	v_cvt_f32_u32_e32 v34, v34
	s_movk_i32 s0, 0xffc5
	v_cmp_lt_i32_e32 vcc, s0, v68
	v_mul_f32_e32 v16, v17, v16
	s_nop 2
	v_mul_f32_e32 v0, 0x3db504f3, v0
	v_cndmask_b32_e32 v17, v101, v66, vcc
	v_mul_f32_e32 v17, v17, v34
	v_exp_f32_e32 v17, v17
	v_cvt_pk_bf16_f32 v16, v16, s0
	v_cmp_ne_u32_e32 vcc, 0, v30
	v_mul_f32_e32 v0, v0, v69
	ds_write_b16 v67, v16 offset:8352
	v_cndmask_b32_e32 v16, 2.0, v17, vcc
	v_cvt_pk_bf16_f32 v0, v0, s0
	v_cmp_ne_u32_e32 vcc, 32, v33
	ds_write_b16 v67, v0 offset:4672
	v_mul_f32_e32 v1, 0x3db504f3, v1
	v_cndmask_b32_e32 v0, 2.0, v48, vcc
	v_mul_f32_e32 v0, v1, v0
	v_cvt_pk_bf16_f32 v0, v0, s0
	v_cmp_ne_u32_e32 vcc, 32, v32
	ds_write_b16 v67, v0 offset:4816
	v_mul_f32_e32 v1, 0x3db504f3, v2
	v_cndmask_b32_e32 v0, 2.0, v49, vcc
	v_mul_f32_e32 v0, v1, v0
	v_cvt_pk_bf16_f32 v0, v0, s0
	v_cmp_ne_u32_e32 vcc, 32, v18
	ds_write_b16 v67, v0 offset:4960
	v_mul_f32_e32 v1, 0x3db504f3, v3
	v_cndmask_b32_e32 v0, 2.0, v50, vcc
	v_mul_f32_e32 v0, v1, v0
	v_cvt_pk_bf16_f32 v0, v0, s0
	v_cmp_ne_u32_e32 vcc, 32, v19
	ds_write_b16 v67, v0 offset:5104
	v_mul_f32_e32 v1, 0x3db504f3, v4
	v_cndmask_b32_e32 v0, 2.0, v51, vcc
	v_mul_f32_e32 v0, v1, v0
	v_cvt_pk_bf16_f32 v0, v0, s0
	v_cmp_ne_u32_e32 vcc, 32, v20
	ds_write_b16 v67, v0 offset:5824
	v_mul_f32_e32 v1, 0x3db504f3, v5
	v_cndmask_b32_e32 v0, 2.0, v52, vcc
	v_mul_f32_e32 v0, v1, v0
	v_cvt_pk_bf16_f32 v0, v0, s0
	v_cmp_ne_u32_e32 vcc, 32, v21
	ds_write_b16 v67, v0 offset:5968
	v_mul_f32_e32 v1, 0x3db504f3, v6
	v_cndmask_b32_e32 v0, 2.0, v53, vcc
	v_mul_f32_e32 v0, v1, v0
	v_cvt_pk_bf16_f32 v0, v0, s0
	v_cmp_ne_u32_e32 vcc, 32, v22
	ds_write_b16 v67, v0 offset:6112
	v_mul_f32_e32 v1, 0x3db504f3, v7
	v_cndmask_b32_e32 v0, 2.0, v54, vcc
	v_mul_f32_e32 v0, v1, v0
	v_cvt_pk_bf16_f32 v0, v0, s0
	v_cmp_ne_u32_e32 vcc, 32, v23
	ds_write_b16 v67, v0 offset:6256
	v_mul_f32_e32 v1, 0x3db504f3, v8
	v_cndmask_b32_e32 v0, 2.0, v55, vcc
	v_mul_f32_e32 v0, v1, v0
	v_cvt_pk_bf16_f32 v0, v0, s0
	v_cmp_ne_u32_e32 vcc, 32, v24
	ds_write_b16 v67, v0 offset:6976
	v_mul_f32_e32 v1, 0x3db504f3, v9
	v_cndmask_b32_e32 v0, 2.0, v56, vcc
	v_mul_f32_e32 v0, v1, v0
	v_cvt_pk_bf16_f32 v0, v0, s0
	v_cmp_ne_u32_e32 vcc, 32, v25
	ds_write_b16 v67, v0 offset:7120
	v_mul_f32_e32 v1, 0x3db504f3, v10
	v_cndmask_b32_e32 v0, 2.0, v57, vcc
	v_mul_f32_e32 v0, v1, v0
	v_cvt_pk_bf16_f32 v0, v0, s0
	v_cmp_ne_u32_e32 vcc, 32, v26
	ds_write_b16 v67, v0 offset:7264
	v_mul_f32_e32 v1, 0x3db504f3, v11
	v_cndmask_b32_e32 v0, 2.0, v58, vcc
	v_mul_f32_e32 v0, v1, v0
	v_cvt_pk_bf16_f32 v0, v0, s0
	v_cmp_ne_u32_e32 vcc, 32, v27
	ds_write_b16 v67, v0 offset:7408
	v_mul_f32_e32 v1, 0x3db504f3, v12
	v_cndmask_b32_e32 v0, 2.0, v59, vcc
	v_mul_f32_e32 v0, v1, v0
	v_cvt_pk_bf16_f32 v0, v0, s0
	v_cmp_ne_u32_e32 vcc, 32, v28
	ds_write_b16 v67, v0 offset:8128
	v_mul_f32_e32 v1, 0x3db504f3, v13
	v_cndmask_b32_e32 v0, 2.0, v60, vcc
	v_mul_f32_e32 v0, v1, v0
	v_cvt_pk_bf16_f32 v0, v0, s0
	v_cmp_ne_u32_e32 vcc, 32, v29
	ds_write_b16 v67, v0 offset:8272
	v_mul_f32_e32 v1, 0x3db504f3, v14
	v_cndmask_b32_e32 v0, 2.0, v61, vcc
	v_mul_f32_e32 v0, v1, v0
	v_cvt_pk_bf16_f32 v0, v0, s0
	v_cmp_ne_u32_e32 vcc, 32, v30
	ds_write_b16 v67, v0 offset:8416
	v_mul_f32_e32 v1, 0x3db504f3, v15
	v_cndmask_b32_e32 v0, 2.0, v62, vcc
	v_mul_f32_e32 v0, v1, v0
	v_cvt_pk_bf16_f32 v0, v0, s0
	ds_write_b16 v67, v0 offset:8560
	v_lshlrev_b32_e32 v0, 1, v64
	v_and_b32_e32 v32, 0x7e, v0
	v_mul_f32_e32 v17, 0x3db504f3, v31
	v_mul_u32_u24_e32 v0, 0xa00, v32
	v_mul_f32_e32 v16, v17, v16
	v_lshlrev_b32_e32 v0, 1, v0
	v_mov_b32_e32 v1, v137
	v_and_b32_e32 v33, 0x60, v65
	v_cvt_pk_bf16_f32 v16, v16, s0
	v_lshl_add_u64 v[0:1], s[42:43], 0, v[0:1]
	v_lshlrev_b32_e32 v2, 1, v33
	v_mov_b32_e32 v3, v137
	ds_write_b16 v67, v16 offset:8496
	v_lshl_add_u64 v[24:25], v[0:1], 0, v[2:3]
	s_movk_i32 s0, 0x1000
	v_add_co_u32_e32 v4, vcc, s0, v24
	global_load_dwordx4 v[0:3], v[24:25], off offset:2880
	s_nop 0
	v_addc_co_u32_e32 v5, vcc, 0, v25, vcc
	global_load_dwordx4 v[4:7], v[4:5], off offset:3904
	s_nop 0
	global_load_dwordx4 v[8:11], v[24:25], off offset:2896
	s_mov_b64 s[0:1], 0x1f40
	v_lshl_add_u64 v[28:29], v[24:25], 0, s[0:1]
	global_load_dwordx4 v[12:15], v[28:29], off offset:16
	global_load_dwordx4 v[16:19], v[24:25], off offset:2912
	global_load_dwordx4 v[20:23], v[28:29], off offset:32
	s_nop 0
	global_load_dwordx4 v[24:27], v[24:25], off offset:2928
	v_lshlrev_b32_e32 v30, 2, v64
	v_and_b32_e32 v34, 0x7c, v30
	global_load_dwordx4 v[28:31], v[28:29], off offset:48
	v_mov_b32_e32 v35, s83
	v_mov_b32_e32 v36, s82
	v_cmp_gt_u32_e32 vcc, 64, v32
	v_mul_u32_u24_e32 v33, 0x90, v33
	s_and_b64 s[0:1], s[40:41], exec
	v_cndmask_b32_e32 v32, v35, v36, vcc
	v_add3_u32 v32, v32, v34, v33
	s_cselect_b32 s34, s2, s23
	s_cmp_eq_u32 s34, 0
	s_cselect_b64 s[0:1], -1, 0
	s_lshl_b32 s2, s22, 3
	s_and_b32 s2, s2, 0xffffff00
	s_lshl_b32 s3, s23, 2
	s_or_b32 s22, s2, s3
	s_and_b64 s[0:1], s[40:41], s[0:1]
	s_addk_i32 s22, 0xfe00
	s_and_b32 s23, s76, -8
	s_and_b64 s[2:3], s[40:41], exec
	s_mov_b32 s2, 0x13c20000
	s_cselect_b32 s2, s2, 0x11c20000
	s_add_u32 s2, s92, s2
	s_addc_u32 s3, s93, 0
	s_and_b64 vcc, exec, s[0:1]
	s_waitcnt vmcnt(7)
	v_lshlrev_b32_e32 v35, 16, v0
	v_and_b32_e32 v0, 0xffff0000, v0
	s_waitcnt vmcnt(6)
	v_lshlrev_b32_e32 v36, 16, v4
	v_and_b32_e32 v4, 0xffff0000, v4
	v_cvt_pk_bf16_f32 v35, v35, v36
	v_cvt_pk_bf16_f32 v0, v0, v4
	ds_write2_b32 v32, v35, v0 offset1:36
	v_lshlrev_b32_e32 v0, 16, v1
	v_lshlrev_b32_e32 v4, 16, v5
	v_cvt_pk_bf16_f32 v0, v0, v4
	v_and_b32_e32 v1, 0xffff0000, v1
	v_and_b32_e32 v4, 0xffff0000, v5
	v_cvt_pk_bf16_f32 v1, v1, v4
	ds_write2_b32 v32, v0, v1 offset0:72 offset1:108
	v_lshlrev_b32_e32 v0, 16, v2
	v_lshlrev_b32_e32 v1, 16, v6
	v_cvt_pk_bf16_f32 v0, v0, v1
	v_and_b32_e32 v1, 0xffff0000, v2
	v_and_b32_e32 v2, 0xffff0000, v6
	v_cvt_pk_bf16_f32 v1, v1, v2
	ds_write2_b32 v32, v0, v1 offset0:144 offset1:180
	v_lshlrev_b32_e32 v0, 16, v3
	v_lshlrev_b32_e32 v1, 16, v7
	v_cvt_pk_bf16_f32 v0, v0, v1
	v_and_b32_e32 v1, 0xffff0000, v3
	v_and_b32_e32 v2, 0xffff0000, v7
	v_cvt_pk_bf16_f32 v1, v1, v2
	ds_write2_b32 v32, v0, v1 offset0:216 offset1:252
	s_waitcnt vmcnt(5)
	v_lshlrev_b32_e32 v0, 16, v8
	s_waitcnt vmcnt(4)
	v_lshlrev_b32_e32 v1, 16, v12
	v_cvt_pk_bf16_f32 v0, v0, v1
	v_and_b32_e32 v1, 0xffff0000, v8
	v_and_b32_e32 v2, 0xffff0000, v12
	v_cvt_pk_bf16_f32 v1, v1, v2
	v_add_u32_e32 v2, 0x400, v32
	ds_write2_b32 v2, v0, v1 offset0:32 offset1:68
	v_lshlrev_b32_e32 v0, 16, v9
	v_lshlrev_b32_e32 v1, 16, v13
	v_cvt_pk_bf16_f32 v0, v0, v1
	v_and_b32_e32 v1, 0xffff0000, v9
	v_and_b32_e32 v3, 0xffff0000, v13
	v_cvt_pk_bf16_f32 v1, v1, v3
	ds_write2_b32 v2, v0, v1 offset0:104 offset1:140
	v_lshlrev_b32_e32 v0, 16, v10
	v_lshlrev_b32_e32 v1, 16, v14
	v_cvt_pk_bf16_f32 v0, v0, v1
	v_and_b32_e32 v1, 0xffff0000, v10
	v_and_b32_e32 v3, 0xffff0000, v14
	v_cvt_pk_bf16_f32 v1, v1, v3
	ds_write2_b32 v2, v0, v1 offset0:176 offset1:212
	v_lshlrev_b32_e32 v0, 16, v11
	v_lshlrev_b32_e32 v1, 16, v15
	v_cvt_pk_bf16_f32 v0, v0, v1
	v_and_b32_e32 v1, 0xffff0000, v11
	v_and_b32_e32 v2, 0xffff0000, v15
	v_cvt_pk_bf16_f32 v1, v1, v2
	v_add_u32_e32 v2, 0x600, v32
	ds_write2_b32 v2, v0, v1 offset0:120 offset1:156
	s_waitcnt vmcnt(3)
	v_lshlrev_b32_e32 v0, 16, v16
	s_waitcnt vmcnt(2)
	v_lshlrev_b32_e32 v1, 16, v20
	v_cvt_pk_bf16_f32 v0, v0, v1
	v_and_b32_e32 v1, 0xffff0000, v16
	v_and_b32_e32 v2, 0xffff0000, v20
	v_cvt_pk_bf16_f32 v1, v1, v2
	v_add_u32_e32 v2, 0x800, v32
	ds_write2_b32 v2, v0, v1 offset0:64 offset1:100
	v_lshlrev_b32_e32 v0, 16, v17
	v_lshlrev_b32_e32 v1, 16, v21
	v_cvt_pk_bf16_f32 v0, v0, v1
	v_and_b32_e32 v1, 0xffff0000, v17
	v_and_b32_e32 v3, 0xffff0000, v21
	v_cvt_pk_bf16_f32 v1, v1, v3
	ds_write2_b32 v2, v0, v1 offset0:136 offset1:172
	v_lshlrev_b32_e32 v0, 16, v18
	v_lshlrev_b32_e32 v1, 16, v22
	v_cvt_pk_bf16_f32 v0, v0, v1
	v_and_b32_e32 v1, 0xffff0000, v18
	v_and_b32_e32 v3, 0xffff0000, v22
	v_cvt_pk_bf16_f32 v1, v1, v3
	ds_write2_b32 v2, v0, v1 offset0:208 offset1:244
	v_lshlrev_b32_e32 v0, 16, v19
	v_lshlrev_b32_e32 v1, 16, v23
	v_cvt_pk_bf16_f32 v0, v0, v1
	v_and_b32_e32 v1, 0xffff0000, v19
	v_and_b32_e32 v2, 0xffff0000, v23
	v_cvt_pk_bf16_f32 v1, v1, v2
	v_add_u32_e32 v2, 0xc00, v32
	ds_write2_b32 v2, v0, v1 offset0:24 offset1:60
	s_waitcnt vmcnt(1)
	v_lshlrev_b32_e32 v0, 16, v24
	s_waitcnt vmcnt(0)
	v_lshlrev_b32_e32 v1, 16, v28
	v_cvt_pk_bf16_f32 v0, v0, v1
	v_and_b32_e32 v1, 0xffff0000, v24
	v_and_b32_e32 v3, 0xffff0000, v28
	v_cvt_pk_bf16_f32 v1, v1, v3
	ds_write2_b32 v2, v0, v1 offset0:96 offset1:132
	v_lshlrev_b32_e32 v0, 16, v25
	v_lshlrev_b32_e32 v1, 16, v29
	v_cvt_pk_bf16_f32 v0, v0, v1
	v_and_b32_e32 v1, 0xffff0000, v25
	v_and_b32_e32 v3, 0xffff0000, v29
	v_cvt_pk_bf16_f32 v1, v1, v3
	ds_write2_b32 v2, v0, v1 offset0:168 offset1:204
	v_lshlrev_b32_e32 v0, 16, v26
	v_lshlrev_b32_e32 v1, 16, v30
	v_cvt_pk_bf16_f32 v0, v0, v1
	v_and_b32_e32 v1, 0xffff0000, v26
	v_and_b32_e32 v2, 0xffff0000, v30
	v_cvt_pk_bf16_f32 v1, v1, v2
	v_add_u32_e32 v2, 0xe00, v32
	ds_write2_b32 v2, v0, v1 offset0:112 offset1:148
	v_lshlrev_b32_e32 v0, 16, v27
	v_lshlrev_b32_e32 v1, 16, v31
	v_cvt_pk_bf16_f32 v0, v0, v1
	v_and_b32_e32 v1, 0xffff0000, v27
	v_and_b32_e32 v2, 0xffff0000, v31
	v_cvt_pk_bf16_f32 v1, v1, v2
	v_add_u32_e32 v2, 0x1000, v32
	ds_write2_b32 v2, v0, v1 offset0:56 offset1:92
	s_waitcnt lgkmcnt(0)
	s_barrier
	ds_read_b128 v[0:3], v97
	ds_read_b128 v[4:7], v98 offset:36864
	ds_read_b128 v[68:71], v97 offset:32
	ds_read_b128 v[72:75], v98 offset:36896
	ds_read_b128 v[16:19], v98 offset:41472
	ds_read_b128 v[76:79], v98 offset:41504
	s_waitcnt lgkmcnt(4)
	v_mfma_f32_32x32x16_bf16 v[32:47], v[0:3], v[4:7], 0
	ds_read_b128 v[20:23], v97 offset:4608
	ds_read_b128 v[84:87], v97 offset:4640
	s_waitcnt lgkmcnt(3)
	v_mfma_f32_32x32x16_bf16 v[48:63], v[0:3], v[16:19], 0
	s_waitcnt lgkmcnt(1)
	v_mfma_f32_32x32x16_bf16 v[0:15], v[20:23], v[4:7], 0
	v_mfma_f32_32x32x16_bf16 v[16:31], v[20:23], v[16:19], 0
	v_mfma_f32_32x32x16_bf16 v[32:47], v[68:71], v[72:75], v[32:47]
	v_mfma_f32_32x32x16_bf16 v[48:63], v[68:71], v[76:79], v[48:63]
	s_waitcnt lgkmcnt(0)
	v_mfma_f32_32x32x16_bf16 v[0:15], v[84:87], v[72:75], v[0:15]
	v_mfma_f32_32x32x16_bf16 v[16:31], v[84:87], v[76:79], v[16:31]
	ds_read_b128 v[68:71], v97 offset:64
	ds_read_b128 v[72:75], v98 offset:36928
	ds_read_b128 v[76:79], v97 offset:96
	ds_read_b128 v[84:87], v98 offset:36960
	ds_read_b128 v[88:91], v98 offset:41536
	ds_read_b128 v[104:107], v98 offset:41568
	s_waitcnt lgkmcnt(4)
	v_mfma_f32_32x32x16_bf16 v[32:47], v[68:71], v[72:75], v[32:47]
	s_waitcnt lgkmcnt(1)
	v_mfma_f32_32x32x16_bf16 v[48:63], v[68:71], v[88:91], v[48:63]
	ds_read_b128 v[68:71], v97 offset:4672
	ds_read_b128 v[108:111], v97 offset:4704
	s_waitcnt lgkmcnt(1)
	v_mfma_f32_32x32x16_bf16 v[0:15], v[68:71], v[72:75], v[0:15]
	v_mfma_f32_32x32x16_bf16 v[16:31], v[68:71], v[88:91], v[16:31]
	v_mfma_f32_32x32x16_bf16 v[32:47], v[76:79], v[84:87], v[32:47]
	v_mfma_f32_32x32x16_bf16 v[48:63], v[76:79], v[104:107], v[48:63]
	s_waitcnt lgkmcnt(0)
	v_mfma_f32_32x32x16_bf16 v[0:15], v[108:111], v[84:87], v[0:15]
	ds_read_b128 v[68:71], v97 offset:18432
	ds_read_b128 v[72:75], v98 offset:55296
	ds_read_b128 v[76:79], v97 offset:18464
	ds_read_b128 v[84:87], v98 offset:55328
	v_mfma_f32_32x32x16_bf16 v[16:31], v[108:111], v[104:107], v[16:31]
	ds_read_b128 v[88:91], v98 offset:59904
	ds_read_b128 v[104:107], v98 offset:59936
	s_waitcnt lgkmcnt(4)
	v_mfma_f32_32x32x16_bf16 v[32:47], v[68:71], v[72:75], v[32:47]
	s_waitcnt lgkmcnt(1)
	v_mfma_f32_32x32x16_bf16 v[48:63], v[68:71], v[88:91], v[48:63]
	ds_read_b128 v[68:71], v97 offset:23040
	ds_read_b128 v[108:111], v97 offset:23072
	s_waitcnt lgkmcnt(1)
	v_mfma_f32_32x32x16_bf16 v[0:15], v[68:71], v[72:75], v[0:15]
	v_mfma_f32_32x32x16_bf16 v[16:31], v[68:71], v[88:91], v[16:31]
	v_mfma_f32_32x32x16_bf16 v[32:47], v[76:79], v[84:87], v[32:47]
	v_mfma_f32_32x32x16_bf16 v[48:63], v[76:79], v[104:107], v[48:63]
	s_waitcnt lgkmcnt(0)
	v_mfma_f32_32x32x16_bf16 v[0:15], v[108:111], v[84:87], v[0:15]
	ds_read_b128 v[68:71], v97 offset:18496
	ds_read_b128 v[72:75], v98 offset:55360
	ds_read_b128 v[76:79], v97 offset:18528
	ds_read_b128 v[84:87], v98 offset:55392
	v_mfma_f32_32x32x16_bf16 v[16:31], v[108:111], v[104:107], v[16:31]
	ds_read_b128 v[88:91], v98 offset:59968
	ds_read_b128 v[108:111], v98 offset:60000
	v_or_b32_e32 v105, 32, v102
	v_or_b32_e32 v106, 64, v102
	v_or_b32_e32 v104, 0x60, v102
	v_add_u32_e32 v107, s24, v82
	s_waitcnt lgkmcnt(4)
	v_mfma_f32_32x32x16_bf16 v[32:47], v[68:71], v[72:75], v[32:47]
	s_waitcnt lgkmcnt(1)
	v_mfma_f32_32x32x16_bf16 v[48:63], v[68:71], v[88:91], v[48:63]
	ds_read_b128 v[68:71], v97 offset:23104
	ds_read_b128 v[112:115], v97 offset:23136
	s_waitcnt lgkmcnt(0)
	s_barrier
	v_mfma_f32_32x32x16_bf16 v[0:15], v[68:71], v[72:75], v[0:15]
	v_mfma_f32_32x32x16_bf16 v[16:31], v[68:71], v[88:91], v[16:31]
	v_lshlrev_b32_e32 v90, 8, v102
	v_lshlrev_b32_e32 v88, 8, v105
	v_mfma_f32_32x32x16_bf16 v[32:47], v[76:79], v[84:87], v[32:47]
	v_mfma_f32_32x32x16_bf16 v[48:63], v[76:79], v[108:111], v[48:63]
	v_mfma_f32_32x32x16_bf16 v[0:15], v[112:115], v[84:87], v[0:15]
	v_lshlrev_b32_e32 v86, 8, v106
	v_lshlrev_b32_e32 v84, 8, v104
	v_mfma_f32_32x32x16_bf16 v[16:31], v[112:115], v[108:111], v[16:31]
	s_cbranch_vccnz .LBB0_634
	v_mov_b32_e32 v83, v137
	v_lshl_add_u64 v[64:65], s[42:43], 0, v[82:83]
	v_lshl_add_u64 v[70:71], v[64:65], 0, v[80:81]
	v_lshl_add_u64 v[154:155], v[70:71], 0, s[8:9]
	v_lshl_add_u64 v[156:157], v[70:71], 0, s[10:11]
	v_lshl_add_u64 v[158:159], v[70:71], 0, s[12:13]
	global_load_dwordx4 v[116:119], v[70:71], off offset:832
	global_load_dwordx4 v[120:123], v[154:155], off offset:832
	global_load_dwordx4 v[124:127], v[156:157], off offset:832
	global_load_dwordx4 v[142:145], v[158:159], off offset:832
	global_load_dwordx4 v[146:149], v[70:71], off offset:960
	global_load_dwordx4 v[150:153], v[154:155], off offset:960
	global_load_dwordx4 v[160:163], v[156:157], off offset:960
	global_load_dwordx4 v[164:167], v[158:159], off offset:960
	v_add_u32_e32 v64, 1, v102
	v_cvt_f32_ubyte0_e32 v64, v64
	v_mul_f32_e32 v64, v66, v64
	v_exp_f32_e32 v68, v64
	v_mad_u32_u24 v67, v105, s5, v107
	s_and_b64 s[0:1], s[40:41], exec
	s_cselect_b32 s0, s23, s22
	s_or_b32 s0, s0, s78
	s_ashr_i32 s1, s0, 31
	s_lshl_b64 s[0:1], s[0:1], 15
	s_add_u32 s0, s2, s0
	s_addc_u32 s1, s3, s1
	v_mov_b32_e32 v91, v137
	v_mov_b32_e32 v89, v137
	v_mov_b32_e32 v87, v137
	v_mov_b32_e32 v85, v137
	s_movk_i32 s4, 0x90
	s_waitcnt vmcnt(7)
	v_mov_b32_e32 v72, v116
	v_mov_b32_e32 v73, v117
	v_mov_b32_e32 v74, v118
	v_mov_b32_e32 v75, v119
	v_lshlrev_b32_e32 v64, 16, v72
	v_and_b32_e32 v65, 0xffff0000, v72
	v_pk_mul_f32 v[64:65], v[68:69], v[64:65] op_sel_hi:[0,1]
	v_cvt_pk_bf16_f32 v72, v64, v65
	v_lshlrev_b32_e32 v64, 16, v73
	v_and_b32_e32 v65, 0xffff0000, v73
	v_pk_mul_f32 v[64:65], v[68:69], v[64:65] op_sel_hi:[0,1]
	v_cvt_pk_bf16_f32 v73, v64, v65
	v_lshlrev_b32_e32 v64, 16, v74
	v_and_b32_e32 v65, 0xffff0000, v74
	v_pk_mul_f32 v[64:65], v[68:69], v[64:65] op_sel_hi:[0,1]
	v_cvt_pk_bf16_f32 v74, v64, v65
	v_lshlrev_b32_e32 v64, 16, v75
	v_and_b32_e32 v65, 0xffff0000, v75
	v_pk_mul_f32 v[64:65], v[68:69], v[64:65] op_sel_hi:[0,1]
	v_cvt_pk_bf16_f32 v75, v64, v65
	v_add_u32_e32 v69, v107, v103
	ds_write_b128 v69, v[72:75]
	v_lshl_add_u64 v[74:75], v[70:71], 0, s[8:9]
	v_add_u32_e32 v64, 33, v102
	v_cvt_f32_ubyte0_e32 v64, v64
	v_mul_f32_e32 v64, v66, v64
	v_exp_f32_e32 v72, v64
	s_waitcnt vmcnt(6)
	v_mov_b32_e32 v76, v120
	v_mov_b32_e32 v77, v121
	v_mov_b32_e32 v78, v122
	v_mov_b32_e32 v79, v123
	v_lshlrev_b32_e32 v64, 16, v76
	v_and_b32_e32 v65, 0xffff0000, v76
	v_pk_mul_f32 v[64:65], v[72:73], v[64:65] op_sel_hi:[0,1]
	v_cvt_pk_bf16_f32 v76, v64, v65
	v_lshlrev_b32_e32 v64, 16, v77
	v_and_b32_e32 v65, 0xffff0000, v77
	v_pk_mul_f32 v[64:65], v[72:73], v[64:65] op_sel_hi:[0,1]
	v_cvt_pk_bf16_f32 v77, v64, v65
	v_lshlrev_b32_e32 v64, 16, v78
	v_and_b32_e32 v65, 0xffff0000, v78
	v_pk_mul_f32 v[64:65], v[72:73], v[64:65] op_sel_hi:[0,1]
	v_cvt_pk_bf16_f32 v78, v64, v65
	v_lshlrev_b32_e32 v64, 16, v79
	v_and_b32_e32 v65, 0xffff0000, v79
	v_pk_mul_f32 v[64:65], v[72:73], v[64:65] op_sel_hi:[0,1]
	v_cvt_pk_bf16_f32 v79, v64, v65
	ds_write_b128 v67, v[76:79]
	v_lshl_add_u64 v[78:79], v[70:71], 0, s[10:11]
	v_add_u32_e32 v64, 0x41, v102
	v_cvt_f32_ubyte0_e32 v64, v64
	v_mul_f32_e32 v64, v66, v64
	v_exp_f32_e32 v76, v64
	v_add_u32_e32 v73, 0x61, v102
	v_cvt_f32_ubyte0_e32 v73, v73
	v_mul_f32_e32 v66, v66, v73
	v_exp_f32_e32 v66, v66
	s_waitcnt vmcnt(5)
	v_mov_b32_e32 v108, v124
	v_mov_b32_e32 v109, v125
	v_mov_b32_e32 v110, v126
	v_mov_b32_e32 v111, v127
	v_lshlrev_b32_e32 v64, 16, v108
	v_and_b32_e32 v65, 0xffff0000, v108
	v_pk_mul_f32 v[64:65], v[76:77], v[64:65] op_sel_hi:[0,1]
	v_cvt_pk_bf16_f32 v108, v64, v65
	v_lshlrev_b32_e32 v64, 16, v109
	v_and_b32_e32 v65, 0xffff0000, v109
	v_pk_mul_f32 v[64:65], v[76:77], v[64:65] op_sel_hi:[0,1]
	v_cvt_pk_bf16_f32 v109, v64, v65
	v_lshlrev_b32_e32 v64, 16, v110
	v_and_b32_e32 v65, 0xffff0000, v110
	v_pk_mul_f32 v[64:65], v[76:77], v[64:65] op_sel_hi:[0,1]
	v_cvt_pk_bf16_f32 v110, v64, v65
	v_lshlrev_b32_e32 v64, 16, v111
	v_and_b32_e32 v65, 0xffff0000, v111
	v_pk_mul_f32 v[64:65], v[76:77], v[64:65] op_sel_hi:[0,1]
	v_cvt_pk_bf16_f32 v111, v64, v65
	v_lshl_add_u64 v[64:65], v[70:71], 0, s[12:13]
	ds_write_b128 v67, v[108:111] offset:4608
	s_waitcnt vmcnt(4)
	v_mov_b32_e32 v108, v142
	v_mov_b32_e32 v109, v143
	v_mov_b32_e32 v110, v144
	v_mov_b32_e32 v111, v145
	v_lshlrev_b32_e32 v112, 16, v108
	v_and_b32_e32 v113, 0xffff0000, v108
	v_pk_mul_f32 v[112:113], v[66:67], v[112:113] op_sel_hi:[0,1]
	v_cvt_pk_bf16_f32 v108, v112, v113
	v_lshlrev_b32_e32 v112, 16, v109
	v_and_b32_e32 v113, 0xffff0000, v109
	v_pk_mul_f32 v[112:113], v[66:67], v[112:113] op_sel_hi:[0,1]
	v_cvt_pk_bf16_f32 v109, v112, v113
	v_lshlrev_b32_e32 v112, 16, v110
	v_and_b32_e32 v113, 0xffff0000, v110
	v_pk_mul_f32 v[112:113], v[66:67], v[112:113] op_sel_hi:[0,1]
	v_cvt_pk_bf16_f32 v110, v112, v113
	v_lshlrev_b32_e32 v112, 16, v111
	v_and_b32_e32 v113, 0xffff0000, v111
	v_pk_mul_f32 v[112:113], v[66:67], v[112:113] op_sel_hi:[0,1]
	v_cvt_pk_bf16_f32 v111, v112, v113
	ds_write_b128 v67, v[108:111] offset:9216
	s_waitcnt vmcnt(3)
	v_mov_b32_e32 v108, v146
	v_mov_b32_e32 v109, v147
	v_mov_b32_e32 v110, v148
	v_mov_b32_e32 v111, v149
	v_lshlrev_b32_e32 v70, 16, v108
	v_and_b32_e32 v71, 0xffff0000, v108
	v_pk_mul_f32 v[70:71], v[68:69], v[70:71] op_sel_hi:[0,1]
	v_cvt_pk_bf16_f32 v108, v70, v71
	v_lshlrev_b32_e32 v70, 16, v109
	v_and_b32_e32 v71, 0xffff0000, v109
	v_pk_mul_f32 v[70:71], v[68:69], v[70:71] op_sel_hi:[0,1]
	v_cvt_pk_bf16_f32 v109, v70, v71
	v_lshlrev_b32_e32 v70, 16, v110
	v_and_b32_e32 v71, 0xffff0000, v110
	v_pk_mul_f32 v[70:71], v[68:69], v[70:71] op_sel_hi:[0,1]
	v_cvt_pk_bf16_f32 v110, v70, v71
	v_lshlrev_b32_e32 v70, 16, v111
	v_and_b32_e32 v71, 0xffff0000, v111
	v_pk_mul_f32 v[70:71], v[68:69], v[70:71] op_sel_hi:[0,1]
	v_cvt_pk_bf16_f32 v111, v70, v71
	ds_write_b128 v69, v[108:111] offset:18432
	s_waitcnt vmcnt(2)
	v_mov_b32_e32 v68, v150
	v_mov_b32_e32 v69, v151
	v_mov_b32_e32 v70, v152
	v_mov_b32_e32 v71, v153
	v_lshlrev_b32_e32 v74, 16, v68
	v_and_b32_e32 v75, 0xffff0000, v68
	v_pk_mul_f32 v[74:75], v[72:73], v[74:75] op_sel_hi:[0,1]
	v_cvt_pk_bf16_f32 v68, v74, v75
	v_lshlrev_b32_e32 v74, 16, v69
	v_and_b32_e32 v75, 0xffff0000, v69
	v_pk_mul_f32 v[74:75], v[72:73], v[74:75] op_sel_hi:[0,1]
	v_cvt_pk_bf16_f32 v69, v74, v75
	v_lshlrev_b32_e32 v74, 16, v70
	v_and_b32_e32 v75, 0xffff0000, v70
	v_pk_mul_f32 v[74:75], v[72:73], v[74:75] op_sel_hi:[0,1]
	v_cvt_pk_bf16_f32 v70, v74, v75
	v_lshlrev_b32_e32 v74, 16, v71
	v_and_b32_e32 v75, 0xffff0000, v71
	v_pk_mul_f32 v[72:73], v[72:73], v[74:75] op_sel_hi:[0,1]
	v_cvt_pk_bf16_f32 v71, v72, v73
	ds_write_b128 v67, v[68:71] offset:18432
	s_waitcnt vmcnt(1)
	v_mov_b32_e32 v68, v160
	v_mov_b32_e32 v69, v161
	v_mov_b32_e32 v70, v162
	v_mov_b32_e32 v71, v163
	v_lshlrev_b32_e32 v72, 16, v68
	v_and_b32_e32 v73, 0xffff0000, v68
	v_pk_mul_f32 v[72:73], v[76:77], v[72:73] op_sel_hi:[0,1]
	v_cvt_pk_bf16_f32 v68, v72, v73
	v_lshlrev_b32_e32 v72, 16, v69
	v_and_b32_e32 v73, 0xffff0000, v69
	v_pk_mul_f32 v[72:73], v[76:77], v[72:73] op_sel_hi:[0,1]
	v_cvt_pk_bf16_f32 v69, v72, v73
	v_lshlrev_b32_e32 v72, 16, v70
	v_and_b32_e32 v73, 0xffff0000, v70
	v_pk_mul_f32 v[72:73], v[76:77], v[72:73] op_sel_hi:[0,1]
	v_cvt_pk_bf16_f32 v70, v72, v73
	v_lshlrev_b32_e32 v72, 16, v71
	v_and_b32_e32 v73, 0xffff0000, v71
	v_pk_mul_f32 v[72:73], v[76:77], v[72:73] op_sel_hi:[0,1]
	v_cvt_pk_bf16_f32 v71, v72, v73
	ds_write_b128 v67, v[68:71] offset:23040
	v_lshl_add_u64 v[76:77], s[0:1], 0, v[136:137]
	v_lshl_add_u64 v[108:109], v[76:77], 0, v[90:91]
	v_lshl_add_u64 v[110:111], v[76:77], 0, v[88:89]
	v_lshl_add_u64 v[112:113], v[76:77], 0, v[86:87]
	global_load_dwordx4 v[72:75], v[112:113], off
	v_lshl_add_u64 v[114:115], v[76:77], 0, v[84:85]
	global_load_dwordx4 v[76:79], v[114:115], off
	s_waitcnt vmcnt(2)
	v_mov_b32_e32 v68, v164
	v_mov_b32_e32 v69, v165
	v_mov_b32_e32 v70, v166
	v_mov_b32_e32 v71, v167
	v_lshlrev_b32_e32 v64, 16, v68
	v_and_b32_e32 v65, 0xffff0000, v68
	v_pk_mul_f32 v[64:65], v[66:67], v[64:65] op_sel_hi:[0,1]
	v_cvt_pk_bf16_f32 v68, v64, v65
	v_lshlrev_b32_e32 v64, 16, v69
	v_and_b32_e32 v65, 0xffff0000, v69
	v_pk_mul_f32 v[64:65], v[66:67], v[64:65] op_sel_hi:[0,1]
	v_cvt_pk_bf16_f32 v69, v64, v65
	v_lshlrev_b32_e32 v64, 16, v70
	v_and_b32_e32 v65, 0xffff0000, v70
	v_pk_mul_f32 v[64:65], v[66:67], v[64:65] op_sel_hi:[0,1]
	v_cvt_pk_bf16_f32 v70, v64, v65
	v_lshlrev_b32_e32 v64, 16, v71
	v_and_b32_e32 v65, 0xffff0000, v71
	v_pk_mul_f32 v[64:65], v[66:67], v[64:65] op_sel_hi:[0,1]
	v_cvt_pk_bf16_f32 v71, v64, v65
	ds_write_b128 v67, v[68:71] offset:27648
	global_load_dwordx4 v[64:67], v[108:109], off
	global_load_dwordx4 v[68:71], v[110:111], off
	s_waitcnt vmcnt(1)
	ds_write_b128 v99, v[64:67] offset:36864
	s_waitcnt vmcnt(0)
	ds_write_b128 v99, v[68:71] offset:41472
	ds_write_b128 v99, v[72:75] offset:46080
	ds_write_b128 v99, v[76:79] offset:50688
	global_load_dwordx4 v[64:67], v[108:109], off offset:128
	global_load_dwordx4 v[68:71], v[110:111], off offset:128
	global_load_dwordx4 v[72:75], v[112:113], off offset:128
	global_load_dwordx4 v[76:79], v[114:115], off offset:128
	s_waitcnt vmcnt(3)
	ds_write_b128 v99, v[64:67] offset:55296
	s_waitcnt vmcnt(2)
	ds_write_b128 v99, v[68:71] offset:59904
	s_waitcnt vmcnt(1)
	ds_write_b128 v99, v[72:75] offset:64512
	s_waitcnt vmcnt(0)
	ds_write_b128 v100, v[76:79] offset:13824
	s_waitcnt lgkmcnt(0)
	s_barrier
	ds_read_b128 v[64:67], v97 offset:4608
	ds_read_b128 v[68:71], v98 offset:41472
	ds_read_b128 v[72:75], v97
	ds_read_b128 v[76:79], v97 offset:32
	ds_read_b128 v[108:111], v97 offset:4640
	ds_read_b128 v[112:115], v98 offset:36864
	ds_read_b128 v[116:119], v98 offset:36896
	ds_read_b128 v[120:123], v98 offset:41504
	ds_read_b128 v[124:127], v97 offset:64
	ds_read_b128 v[142:145], v97 offset:4672
	ds_read_b128 v[146:149], v98 offset:36928
	ds_read_b128 v[150:153], v98 offset:41536
	ds_read_b128 v[154:157], v97 offset:96
	ds_read_b128 v[158:161], v97 offset:4704
	ds_read_b128 v[162:165], v98 offset:36960
	ds_read_b128 v[166:169], v98 offset:41568
	s_waitcnt lgkmcnt(10)
	v_mfma_f32_32x32x16_bf16 v[32:47], v[72:75], v[112:115], v[32:47]
	v_mfma_f32_32x32x16_bf16 v[48:63], v[72:75], v[68:71], v[48:63]
	v_mfma_f32_32x32x16_bf16 v[0:15], v[64:67], v[112:115], v[0:15]
	v_mfma_f32_32x32x16_bf16 v[16:31], v[64:67], v[68:71], v[16:31]
	s_waitcnt lgkmcnt(9)
	v_mfma_f32_32x32x16_bf16 v[32:47], v[76:79], v[116:119], v[32:47]
	s_waitcnt lgkmcnt(8)
	v_mfma_f32_32x32x16_bf16 v[48:63], v[76:79], v[120:123], v[48:63]
	v_mfma_f32_32x32x16_bf16 v[0:15], v[108:111], v[116:119], v[0:15]
	v_mfma_f32_32x32x16_bf16 v[16:31], v[108:111], v[120:123], v[16:31]
	s_waitcnt lgkmcnt(5)
	v_mfma_f32_32x32x16_bf16 v[32:47], v[124:127], v[146:149], v[32:47]
	s_waitcnt lgkmcnt(4)
	v_mfma_f32_32x32x16_bf16 v[48:63], v[124:127], v[150:153], v[48:63]
	v_mfma_f32_32x32x16_bf16 v[0:15], v[142:145], v[146:149], v[0:15]
	v_mfma_f32_32x32x16_bf16 v[16:31], v[142:145], v[150:153], v[16:31]
	s_waitcnt lgkmcnt(1)
	v_mfma_f32_32x32x16_bf16 v[32:47], v[154:157], v[162:165], v[32:47]
	s_waitcnt lgkmcnt(0)
	v_mfma_f32_32x32x16_bf16 v[48:63], v[154:157], v[166:169], v[48:63]
	v_mfma_f32_32x32x16_bf16 v[0:15], v[158:161], v[162:165], v[0:15]
	v_mfma_f32_32x32x16_bf16 v[16:31], v[158:161], v[166:169], v[16:31]
	ds_read_b128 v[64:67], v97 offset:23040
	ds_read_b128 v[68:71], v98 offset:59904
	ds_read_b128 v[72:75], v97 offset:18432
	ds_read_b128 v[76:79], v97 offset:18464
	ds_read_b128 v[108:111], v97 offset:23072
	ds_read_b128 v[112:115], v98 offset:55296
	ds_read_b128 v[116:119], v98 offset:55328
	ds_read_b128 v[120:123], v98 offset:59936
	ds_read_b128 v[124:127], v97 offset:18496
	ds_read_b128 v[142:145], v97 offset:23104
	ds_read_b128 v[146:149], v98 offset:55360
	ds_read_b128 v[150:153], v98 offset:59968
	ds_read_b128 v[154:157], v97 offset:18528
	ds_read_b128 v[158:161], v97 offset:23136
	ds_read_b128 v[162:165], v98 offset:55392
	ds_read_b128 v[166:169], v98 offset:60000
	s_waitcnt lgkmcnt(0)
	s_barrier
	v_mfma_f32_32x32x16_bf16 v[32:47], v[72:75], v[112:115], v[32:47]
	v_mfma_f32_32x32x16_bf16 v[48:63], v[72:75], v[68:71], v[48:63]
	v_mfma_f32_32x32x16_bf16 v[0:15], v[64:67], v[112:115], v[0:15]
	v_mfma_f32_32x32x16_bf16 v[16:31], v[64:67], v[68:71], v[16:31]
	v_mfma_f32_32x32x16_bf16 v[32:47], v[76:79], v[116:119], v[32:47]
	v_mfma_f32_32x32x16_bf16 v[48:63], v[76:79], v[120:123], v[48:63]
	v_mfma_f32_32x32x16_bf16 v[0:15], v[108:111], v[116:119], v[0:15]
	v_mfma_f32_32x32x16_bf16 v[16:31], v[108:111], v[120:123], v[16:31]
	v_mfma_f32_32x32x16_bf16 v[32:47], v[124:127], v[146:149], v[32:47]
	v_mfma_f32_32x32x16_bf16 v[48:63], v[124:127], v[150:153], v[48:63]
	v_mfma_f32_32x32x16_bf16 v[0:15], v[142:145], v[146:149], v[0:15]
	v_mfma_f32_32x32x16_bf16 v[16:31], v[142:145], v[150:153], v[16:31]
	v_mfma_f32_32x32x16_bf16 v[32:47], v[154:157], v[162:165], v[32:47]
	v_mfma_f32_32x32x16_bf16 v[48:63], v[154:157], v[166:169], v[48:63]
	v_mfma_f32_32x32x16_bf16 v[0:15], v[158:161], v[162:165], v[0:15]
	v_mfma_f32_32x32x16_bf16 v[16:31], v[158:161], v[166:169], v[16:31]
	s_branch .LBB0_635
